# spatial phase: hoisted loads + counted waits; UG stored in fragment order (1KiB coalesced stores/loads)
# speedup vs baseline: 1.0198x; 1.0198x over previous
; #define PG8_STAGE(bufoff, gbase, voff) do { _Pragma("unroll") for (int _i = 0; _i < 2; ++_i) \
;         __builtin_amdgcn_global_load_lds((const __attribute__((address_space(1))) unsigned*)((const char*)(gbase) + (voff)[_i]), (LAS unsigned*)(lds + (bufoff) + ldsw + _i * 8192), 16, 0, 0); } while (0)
; #define PG8_LDA(dst, b, h) do { _Pragma("unroll") for (int m = 0; m < 4; ++m) _Pragma("unroll") for (int k = 0; k < 2; ++k) dst[m][k] = *(const LAS bf16x8*)(lds + PG8_SA(b, h) + aoff + m * 2048 + k * 1024); } while (0)
; #define PG8_WAIT_V(n) asm volatile("s_waitcnt vmcnt(" #n ")" ::: "memory")
; template <class Epi>
; __device__ __forceinline__ void gemm_phase(LAS unsigned char* lds, const Gemm g, const StaticOrder& S_in, const Epi& E, int sw) {
;     ...
;         for (int t = 0; t < nt; t += 2) {
;             const bool last = (t == nt - 2);
;             const char* a1 = cA + (size_t)(t + 1) * kstep;
;             const char* a2 = last ? nA : cA + (size_t)(t + 2) * kstep; const char* b2 = last ? nB : cB + (size_t)(t + 2) * kstep;
;             const char* a3 = a2 + kstep; const char* b3 = b2 + kstep;
;             PG8_LDB(B0, 0, 0); PG8_SCHED; PG8_LDA(At, 0, 0); PG8_STAGE(PG8_SA(1, 1), a1 + hstepA, voffA);
;             PG8_WAIT_L(8); PG8_BAR; PG8_WAIT_L(0); PG8_MMA(0, 0, At, B0); PG8_BAR; PG8_SCHED;
;             PG8_LDB(B1, 0, 1); PG8_STAGE(PG8_SB(0, 0), b2, voffB);
;             PG8_BAR; PG8_WAIT_L(0); PG8_MMA(0, 1, At, B1); PG8_BAR;
;             PG8_LDA(At, 0, 1); PG8_STAGE(PG8_SA(0, 0), a2, voffA);
;             PG8_BAR; PG8_WAIT_L(0); PG8_MMA(1, 0, At, B0); PG8_BAR; PG8_SCHED;
;             PG8_STAGE(PG8_SB(0, 1), b2 + hstepB, voffB);
;             PG8_WAIT_V(6); PG8_BAR; PG8_MMA(1, 1, At, B1); PG8_BAR;
;             PG8_LDB(B0, 1, 0); PG8_SCHED; PG8_LDA(At, 1, 0); PG8_STAGE(PG8_SA(0, 1), a2 + hstepA, voffA);
;             PG8_WAIT_L(8); PG8_BAR; PG8_WAIT_L(0); PG8_MMA(0, 0, At, B0); PG8_BAR; PG8_SCHED;
;             PG8_LDB(B1, 1, 1); PG8_STAGE(PG8_SB(1, 0), b3, voffB);
;             PG8_BAR; PG8_WAIT_L(0); PG8_MMA(0, 1, At, B1); PG8_BAR;
;             PG8_LDA(At, 1, 1); PG8_STAGE(PG8_SA(1, 0), a3, voffA);
;             PG8_BAR; PG8_WAIT_L(0); PG8_MMA(1, 0, At, B0); PG8_BAR; PG8_SCHED;
;             PG8_STAGE(PG8_SB(1, 1), b3 + hstepB, voffB);
;             PG8_WAIT_V(6); PG8_BAR; PG8_MMA(1, 1, At, B1); PG8_BAR;
.LBB0_756:
	s_add_u32 s26, s24, 0xfffc0080
	s_addc_u32 s27, s25, -1
	s_add_i32 s56, 0, 0x10000
	v_add_u32_e32 v140, s56, v142
	ds_read_b128 v[144:147], v140
	ds_read_b128 v[148:151], v140 offset:1024
	ds_read_b128 v[152:155], v140 offset:2048
	ds_read_b128 v[156:159], v140 offset:3072
	s_cmp_eq_u32 s55, 12
	s_cselect_b32 s29, s17, s27
	s_cselect_b32 s28, s51, s26
	s_cselect_b32 s27, s13, s54
	s_cselect_b32 s26, s52, s53
	v_lshl_add_u64 v[140:141], s[24:25], 0, v[136:137]
	s_add_i32 m0, s23, 0xc000
	ds_read_b128 v[160:163], v143
	ds_read_b128 v[164:167], v143 offset:1024
	ds_read_b128 v[172:175], v143 offset:2048
	ds_read_b128 v[176:179], v143 offset:3072
	ds_read_b128 v[180:183], v143 offset:4096
	ds_read_b128 v[184:187], v143 offset:5120
	ds_read_b128 v[188:191], v143 offset:6144
	ds_read_b128 v[192:195], v143 offset:7168
	global_load_lds_dwordx4 v[140:141], off
	v_lshl_add_u64 v[140:141], s[24:25], 0, v[138:139]
	s_add_i32 m0, s23, 0xe000
	s_nop 0
	global_load_lds_dwordx4 v[140:141], off
	s_waitcnt lgkmcnt(8)
	s_barrier
	s_waitcnt lgkmcnt(0)
	s_setprio 1
	s_waitcnt lgkmcnt(0)
	v_mfma_f32_16x16x32_bf16 v[126:129], v[144:147], v[160:163], v[126:129]
	v_mfma_f32_16x16x32_bf16 v[118:121], v[152:155], v[160:163], v[118:121]
	v_mfma_f32_16x16x32_bf16 v[110:113], v[144:147], v[172:175], v[110:113]
	v_mfma_f32_16x16x32_bf16 v[102:105], v[152:155], v[172:175], v[102:105]
	v_mfma_f32_16x16x32_bf16 v[94:97], v[144:147], v[180:183], v[94:97]
	v_mfma_f32_16x16x32_bf16 v[86:89], v[152:155], v[180:183], v[86:89]
	v_mfma_f32_16x16x32_bf16 v[78:81], v[144:147], v[188:191], v[78:81]
	v_mfma_f32_16x16x32_bf16 v[70:73], v[152:155], v[188:191], v[70:73]
	v_mfma_f32_16x16x32_bf16 v[126:129], v[148:151], v[164:167], v[126:129]
	v_mfma_f32_16x16x32_bf16 v[118:121], v[156:159], v[164:167], v[118:121]
	v_mfma_f32_16x16x32_bf16 v[110:113], v[148:151], v[176:179], v[110:113]
	v_mfma_f32_16x16x32_bf16 v[102:105], v[156:159], v[176:179], v[102:105]
	v_mfma_f32_16x16x32_bf16 v[94:97], v[148:151], v[184:187], v[94:97]
	v_mfma_f32_16x16x32_bf16 v[86:89], v[156:159], v[184:187], v[86:89]
	v_mfma_f32_16x16x32_bf16 v[78:81], v[148:151], v[192:195], v[78:81]
	v_mfma_f32_16x16x32_bf16 v[70:73], v[156:159], v[192:195], v[70:73]
	s_setprio 0
	s_barrier
	s_add_i32 s58, 0, 0x14000
	v_add_u32_e32 v140, s58, v142
	s_add_i32 s56, s56, s41
	ds_read_b128 v[196:199], v140
	ds_read_b128 v[200:203], v140 offset:1024
	ds_read_b128 v[204:207], v140 offset:2048
	ds_read_b128 v[208:211], v140 offset:3072
	v_lshl_add_u64 v[140:141], s[26:27], 0, v[0:1]
	s_mov_b32 m0, s56
	v_lshl_add_u64 v[168:169], s[26:27], 0, v[130:131]
	global_load_lds_dwordx4 v[140:141], off
	s_add_i32 m0, s56, 0x2000
	s_nop 0
	global_load_lds_dwordx4 v[168:169], off
	s_barrier
	s_waitcnt lgkmcnt(0)
	s_setprio 1
	s_waitcnt lgkmcnt(0)
	v_mfma_f32_16x16x32_bf16 v[122:125], v[196:199], v[160:163], v[122:125]
	v_mfma_f32_16x16x32_bf16 v[114:117], v[204:207], v[160:163], v[114:117]
	v_mfma_f32_16x16x32_bf16 v[106:109], v[196:199], v[172:175], v[106:109]
	v_mfma_f32_16x16x32_bf16 v[98:101], v[204:207], v[172:175], v[98:101]
	v_mfma_f32_16x16x32_bf16 v[90:93], v[196:199], v[180:183], v[90:93]
	v_mfma_f32_16x16x32_bf16 v[82:85], v[204:207], v[180:183], v[82:85]
	v_mfma_f32_16x16x32_bf16 v[74:77], v[196:199], v[188:191], v[74:77]
	v_mfma_f32_16x16x32_bf16 v[66:69], v[204:207], v[188:191], v[66:69]
	v_mfma_f32_16x16x32_bf16 v[122:125], v[200:203], v[164:167], v[122:125]
	v_mfma_f32_16x16x32_bf16 v[114:117], v[208:211], v[164:167], v[114:117]
	v_mfma_f32_16x16x32_bf16 v[106:109], v[200:203], v[176:179], v[106:109]
	v_mfma_f32_16x16x32_bf16 v[98:101], v[208:211], v[176:179], v[98:101]
	v_mfma_f32_16x16x32_bf16 v[90:93], v[200:203], v[184:187], v[90:93]
	v_mfma_f32_16x16x32_bf16 v[82:85], v[208:211], v[184:187], v[82:85]
	v_mfma_f32_16x16x32_bf16 v[74:77], v[200:203], v[192:195], v[74:77]
	v_mfma_f32_16x16x32_bf16 v[66:69], v[208:211], v[192:195], v[66:69]
	s_setprio 0
	s_mov_b32 m0, s23
	v_lshl_add_u64 v[212:213], s[28:29], 0, v[134:135]
	s_barrier
	ds_read_b128 v[160:163], v143 offset:16384
	ds_read_b128 v[164:167], v143 offset:17408
	ds_read_b128 v[172:175], v143 offset:18432
	ds_read_b128 v[176:179], v143 offset:19456
	ds_read_b128 v[180:183], v143 offset:20480
	ds_read_b128 v[184:187], v143 offset:21504
	ds_read_b128 v[188:191], v143 offset:22528
	ds_read_b128 v[192:195], v143 offset:23552
	global_load_lds_dwordx4 v[212:213], off
	v_lshl_add_u64 v[214:215], s[28:29], 0, v[132:133]
	s_mov_b32 m0, s43
	s_nop 0
	global_load_lds_dwordx4 v[214:215], off
	s_barrier
	s_waitcnt lgkmcnt(0)
	s_setprio 1
	s_waitcnt lgkmcnt(0)
	v_mfma_f32_16x16x32_bf16 v[62:65], v[144:147], v[160:163], v[62:65]
	v_mfma_f32_16x16x32_bf16 v[54:57], v[152:155], v[160:163], v[54:57]
	v_mfma_f32_16x16x32_bf16 v[46:49], v[144:147], v[172:175], v[46:49]
	v_mfma_f32_16x16x32_bf16 v[38:41], v[152:155], v[172:175], v[38:41]
	v_mfma_f32_16x16x32_bf16 v[30:33], v[144:147], v[180:183], v[30:33]
	v_mfma_f32_16x16x32_bf16 v[22:25], v[152:155], v[180:183], v[22:25]
	v_mfma_f32_16x16x32_bf16 v[14:17], v[144:147], v[188:191], v[14:17]
	v_mfma_f32_16x16x32_bf16 v[6:9], v[152:155], v[188:191], v[6:9]
	v_mfma_f32_16x16x32_bf16 v[62:65], v[148:151], v[164:167], v[62:65]
	v_mfma_f32_16x16x32_bf16 v[54:57], v[156:159], v[164:167], v[54:57]
	v_mfma_f32_16x16x32_bf16 v[46:49], v[148:151], v[176:179], v[46:49]
	v_mfma_f32_16x16x32_bf16 v[38:41], v[156:159], v[176:179], v[38:41]
	v_mfma_f32_16x16x32_bf16 v[30:33], v[148:151], v[184:187], v[30:33]
	v_mfma_f32_16x16x32_bf16 v[22:25], v[156:159], v[184:187], v[22:25]
	v_mfma_f32_16x16x32_bf16 v[14:17], v[148:151], v[192:195], v[14:17]
	v_mfma_f32_16x16x32_bf16 v[6:9], v[156:159], v[192:195], v[6:9]
	s_setprio 0
	s_barrier
; #define PG8_STAGE(bufoff, gbase, voff) do { _Pragma("unroll") for (int _i = 0; _i < 2; ++_i) \
;         __builtin_amdgcn_global_load_lds((const __attribute__((address_space(1))) unsigned*)((const char*)(gbase) + (voff)[_i]), (LAS unsigned*)(lds + (bufoff) + ldsw + _i * 8192), 16, 0, 0); } while (0)
; #define PG8_LDA(dst, b, h) do { _Pragma("unroll") for (int m = 0; m < 4; ++m) _Pragma("unroll") for (int k = 0; k < 2; ++k) dst[m][k] = *(const LAS bf16x8*)(lds + PG8_SA(b, h) + aoff + m * 2048 + k * 1024); } while (0)
; #define PG8_LDB(dst, b, h) do { _Pragma("unroll") for (int n = 0; n < 2; ++n) _Pragma("unroll") for (int k = 0; k < 2; ++k) dst[n][k] = *(const LAS bf16x8*)(lds + PG8_SB(b, h) + boff + n * 2048 + k * 1024); } while (0)
; #define PG8_WAIT_V(n) asm volatile("s_waitcnt vmcnt(" #n ")" ::: "memory")
; #define PG8_WAIT_L(n) asm volatile("s_waitcnt lgkmcnt(" #n ")" ::: "memory")
; #define PG8_BAR __builtin_amdgcn_s_barrier()
; template <class Epi>
; __device__ __forceinline__ void gemm_phase(LAS unsigned char* lds, const Gemm g, const StaticOrder& S_in, const Epi& E, int sw) {
;     ...
;             PG8_LDB(B0, 0, 0); PG8_SCHED; PG8_LDA(At, 0, 0); PG8_STAGE(PG8_SA(1, 1), a1 + hstepA, voffA);
;             PG8_WAIT_L(8); PG8_BAR; PG8_WAIT_L(0); PG8_MMA(0, 0, At, B0); PG8_BAR; PG8_SCHED;
;             PG8_LDB(B1, 0, 1); PG8_STAGE(PG8_SB(0, 0), b2, voffB);
;             PG8_BAR; PG8_WAIT_L(0); PG8_MMA(0, 1, At, B1); PG8_BAR;
;             PG8_LDA(At, 0, 1); PG8_STAGE(PG8_SA(0, 0), a2, voffA);
;             PG8_BAR; PG8_WAIT_L(0); PG8_MMA(1, 0, At, B0); PG8_BAR; PG8_SCHED;
;             PG8_STAGE(PG8_SB(0, 1), b2 + hstepB, voffB);
;             PG8_WAIT_V(6); PG8_BAR; PG8_MMA(1, 1, At, B1); PG8_BAR;
;             PG8_LDB(B0, 1, 0); PG8_SCHED; PG8_LDA(At, 1, 0); PG8_STAGE(PG8_SA(0, 1), a2 + hstepA, voffA);
;             PG8_WAIT_L(8); PG8_BAR; PG8_WAIT_L(0); PG8_MMA(0, 0, At, B0); PG8_BAR; PG8_SCHED;
;             PG8_LDB(B1, 1, 1); PG8_STAGE(PG8_SB(1, 0), b3, voffB);
;             PG8_BAR; PG8_WAIT_L(0); PG8_MMA(0, 1, At, B1); PG8_BAR;
;             PG8_LDA(At, 1, 1); PG8_STAGE(PG8_SA(1, 0), a3, voffA);
;             PG8_BAR; PG8_WAIT_L(0); PG8_MMA(1, 0, At, B0); PG8_BAR; PG8_SCHED;
;             PG8_STAGE(PG8_SB(1, 1), b3 + hstepB, voffB);
;             PG8_WAIT_V(6); PG8_BAR; PG8_MMA(1, 1, At, B1); PG8_BAR;
	s_add_u32 s56, s26, 0x40000
	s_addc_u32 s57, s27, 0
	s_add_i32 s58, s58, s41
	v_lshl_add_u64 v[144:145], s[56:57], 0, v[0:1]
	s_mov_b32 m0, s58
	s_nop 0
	global_load_lds_dwordx4 v[144:145], off
	v_lshl_add_u64 v[144:145], s[56:57], 0, v[130:131]
	s_add_i32 m0, s58, 0x2000
	s_nop 0
	global_load_lds_dwordx4 v[144:145], off
	s_waitcnt vmcnt(6)
	s_barrier
	s_setprio 1
	v_mfma_f32_16x16x32_bf16 v[58:61], v[196:199], v[160:163], v[58:61]
	v_mfma_f32_16x16x32_bf16 v[50:53], v[204:207], v[160:163], v[50:53]
	v_mfma_f32_16x16x32_bf16 v[42:45], v[196:199], v[172:175], v[42:45]
	v_mfma_f32_16x16x32_bf16 v[34:37], v[204:207], v[172:175], v[34:37]
	v_mfma_f32_16x16x32_bf16 v[26:29], v[196:199], v[180:183], v[26:29]
	v_mfma_f32_16x16x32_bf16 v[18:21], v[204:207], v[180:183], v[18:21]
	v_mfma_f32_16x16x32_bf16 v[10:13], v[196:199], v[188:191], v[10:13]
	v_mfma_f32_16x16x32_bf16 v[2:5], v[204:207], v[188:191], v[2:5]
	v_mfma_f32_16x16x32_bf16 v[58:61], v[200:203], v[164:167], v[58:61]
	v_mfma_f32_16x16x32_bf16 v[50:53], v[208:211], v[164:167], v[50:53]
	v_mfma_f32_16x16x32_bf16 v[42:45], v[200:203], v[176:179], v[42:45]
	v_mfma_f32_16x16x32_bf16 v[34:37], v[208:211], v[176:179], v[34:37]
	v_mfma_f32_16x16x32_bf16 v[26:29], v[200:203], v[184:187], v[26:29]
	v_mfma_f32_16x16x32_bf16 v[18:21], v[208:211], v[184:187], v[18:21]
	v_mfma_f32_16x16x32_bf16 v[10:13], v[200:203], v[192:195], v[10:13]
	v_mfma_f32_16x16x32_bf16 v[2:5], v[208:211], v[192:195], v[2:5]
	s_setprio 0
	s_add_i32 s56, 0, 0x18000
	v_add_u32_e32 v156, s56, v142
	s_barrier
	ds_read_b128 v[144:147], v156
	ds_read_b128 v[148:151], v156 offset:1024
	ds_read_b128 v[152:155], v156 offset:2048
	ds_read_b128 v[156:159], v156 offset:3072
	s_add_u32 s28, s28, 0x40000
	s_addc_u32 s29, s29, 0
	s_mov_b32 m0, s44
	v_lshl_add_u64 v[196:197], s[28:29], 0, v[134:135]
	ds_read_b128 v[160:163], v143 offset:32768
	ds_read_b128 v[164:167], v143 offset:33792
	ds_read_b128 v[172:175], v143 offset:34816
	ds_read_b128 v[176:179], v143 offset:35840
	ds_read_b128 v[180:183], v143 offset:36864
	ds_read_b128 v[184:187], v143 offset:37888
	ds_read_b128 v[188:191], v143 offset:38912
	ds_read_b128 v[192:195], v143 offset:39936
	global_load_lds_dwordx4 v[196:197], off
	v_lshl_add_u64 v[196:197], s[28:29], 0, v[132:133]
	s_mov_b32 m0, s45
	s_nop 0
	global_load_lds_dwordx4 v[196:197], off
	s_waitcnt lgkmcnt(8)
	s_barrier
	s_waitcnt lgkmcnt(0)
	s_setprio 1
	s_waitcnt lgkmcnt(0)
	v_mfma_f32_16x16x32_bf16 v[126:129], v[144:147], v[160:163], v[126:129]
	v_mfma_f32_16x16x32_bf16 v[118:121], v[152:155], v[160:163], v[118:121]
	v_mfma_f32_16x16x32_bf16 v[110:113], v[144:147], v[172:175], v[110:113]
	v_mfma_f32_16x16x32_bf16 v[102:105], v[152:155], v[172:175], v[102:105]
	v_mfma_f32_16x16x32_bf16 v[94:97], v[144:147], v[180:183], v[94:97]
	v_mfma_f32_16x16x32_bf16 v[86:89], v[152:155], v[180:183], v[86:89]
	v_mfma_f32_16x16x32_bf16 v[78:81], v[144:147], v[188:191], v[78:81]
	v_mfma_f32_16x16x32_bf16 v[70:73], v[152:155], v[188:191], v[70:73]
	v_mfma_f32_16x16x32_bf16 v[126:129], v[148:151], v[164:167], v[126:129]
	v_mfma_f32_16x16x32_bf16 v[118:121], v[156:159], v[164:167], v[118:121]
	v_mfma_f32_16x16x32_bf16 v[110:113], v[148:151], v[176:179], v[110:113]
	v_mfma_f32_16x16x32_bf16 v[102:105], v[156:159], v[176:179], v[102:105]
	v_mfma_f32_16x16x32_bf16 v[94:97], v[148:151], v[184:187], v[94:97]
	v_mfma_f32_16x16x32_bf16 v[86:89], v[156:159], v[184:187], v[86:89]
	v_mfma_f32_16x16x32_bf16 v[78:81], v[148:151], v[192:195], v[78:81]
	v_mfma_f32_16x16x32_bf16 v[70:73], v[156:159], v[192:195], v[70:73]
	s_setprio 0
	s_barrier
	s_add_i32 s28, 0, 0x1c000
	s_add_i32 s29, s56, s41
	v_add_u32_e32 v171, s28, v142
	v_lshl_add_u64 v[140:141], v[140:141], 0, s[86:87]
	s_mov_b32 m0, s29
	ds_read_b128 v[196:199], v171
	ds_read_b128 v[200:203], v171 offset:1024
	ds_read_b128 v[204:207], v171 offset:2048
	ds_read_b128 v[208:211], v171 offset:3072
	global_load_lds_dwordx4 v[140:141], off
	v_lshl_add_u64 v[140:141], v[168:169], 0, s[86:87]
	s_add_i32 m0, s29, 0x2000
	s_nop 0
	global_load_lds_dwordx4 v[140:141], off
	s_barrier
	s_waitcnt lgkmcnt(0)
	s_setprio 1
	s_waitcnt lgkmcnt(0)
	v_mfma_f32_16x16x32_bf16 v[122:125], v[196:199], v[160:163], v[122:125]
	v_mfma_f32_16x16x32_bf16 v[114:117], v[204:207], v[160:163], v[114:117]
	v_mfma_f32_16x16x32_bf16 v[106:109], v[196:199], v[172:175], v[106:109]
	v_mfma_f32_16x16x32_bf16 v[98:101], v[204:207], v[172:175], v[98:101]
	v_mfma_f32_16x16x32_bf16 v[90:93], v[196:199], v[180:183], v[90:93]
	v_mfma_f32_16x16x32_bf16 v[82:85], v[204:207], v[180:183], v[82:85]
	v_mfma_f32_16x16x32_bf16 v[74:77], v[196:199], v[188:191], v[74:77]
	v_mfma_f32_16x16x32_bf16 v[66:69], v[204:207], v[188:191], v[66:69]
	v_mfma_f32_16x16x32_bf16 v[122:125], v[200:203], v[164:167], v[122:125]
	v_mfma_f32_16x16x32_bf16 v[114:117], v[208:211], v[164:167], v[114:117]
	v_mfma_f32_16x16x32_bf16 v[106:109], v[200:203], v[176:179], v[106:109]
	v_mfma_f32_16x16x32_bf16 v[98:101], v[208:211], v[176:179], v[98:101]
	v_mfma_f32_16x16x32_bf16 v[90:93], v[200:203], v[184:187], v[90:93]
	v_mfma_f32_16x16x32_bf16 v[82:85], v[208:211], v[184:187], v[82:85]
	v_mfma_f32_16x16x32_bf16 v[74:77], v[200:203], v[192:195], v[74:77]
	v_mfma_f32_16x16x32_bf16 v[66:69], v[208:211], v[192:195], v[66:69]
	s_setprio 0
	s_mov_b32 m0, s46
	v_lshl_add_u64 v[140:141], v[212:213], 0, s[86:87]
	s_barrier
	ds_read_b128 v[160:163], v143 offset:49152
	ds_read_b128 v[164:167], v143 offset:50176
	ds_read_b128 v[172:175], v143 offset:51200
	ds_read_b128 v[176:179], v143 offset:52224
	ds_read_b128 v[180:183], v143 offset:53248
	ds_read_b128 v[184:187], v143 offset:54272
	ds_read_b128 v[188:191], v143 offset:55296
	ds_read_b128 v[192:195], v143 offset:56320
	global_load_lds_dwordx4 v[140:141], off
	v_lshl_add_u64 v[140:141], v[214:215], 0, s[86:87]
	s_mov_b32 m0, s47
	s_nop 0
	global_load_lds_dwordx4 v[140:141], off
	s_barrier
; __device__ __forceinline__ unsigned cvt_pk_bf16(float lo, float hi) { unsigned r; asm volatile("v_cvt_pk_bf16_f32 %0, %1, %2" : "=v"(r) : "v"(lo), "v"(hi)); return r; }
; #define PG8_WAIT_V(n) asm volatile("s_waitcnt vmcnt(" #n ")" ::: "memory")
; template <class Epi>
; __device__ __forceinline__ void gemm_phase(LAS unsigned char* lds, const Gemm g, const StaticOrder& S_in, const Epi& E, int sw) {
;     ...
;             PG8_BAR; PG8_WAIT_L(0); PG8_MMA(1, 0, At, B0); PG8_BAR; PG8_SCHED;
;             PG8_STAGE(PG8_SB(1, 1), b3 + hstepB, voffB);
;             PG8_WAIT_V(6); PG8_BAR; PG8_MMA(1, 1, At, B1); PG8_BAR;
;         }
;         __builtin_amdgcn_sched_barrier(0);
;         E(acc, cur, sw);
;     EPI_ZERO_INIT
;     __device__ __forceinline__ void operator()(AccRef acc, const Unit& u, int sw) const {
;         const int tid_ = ltid(sw), lane_ = tid_ & 63, wr = sw >> 2, wc = sw & 3, fr = lane_ & 15, fq = lane_ >> 4;
;         const int row0 = u.pm * BM + wr * 64 + fr, c0 = u.pn * 128 + wc * 32 + 8 * fq;
; #pragma unroll
;         for (int ai = 0; ai < 2; ++ai)
; #pragma unroll
;             for (int m = 0; m < 4; ++m) { bf16_t* rowp = UG + (size_t)(row0 + ai * HALF + m * 16) * E + c0;
;                 float y[8];
; #pragma unroll
;                 for (int n = 0; n < 2; ++n)
; #pragma unroll
;                     for (int jp = 0; jp < 2; ++jp) {
;                         const f32x2 uu = (f32x2){acc[ai][0][m][n][2 * jp], acc[ai][0][m][n][2 * jp + 1]}, gg = (f32x2){acc[ai][1][m][n][2 * jp], acc[ai][1][m][n][2 * jp + 1]};
;                         const f32x2 za = (uu * uu * 0.044715f + 1.0f) * uu * (-1.44269504f * 1.59576912f), zg = gg * (-1.44269504f);
;                         f32x2 ea, eg; ea.x = __builtin_amdgcn_exp2f(za.x); ea.y = __builtin_amdgcn_exp2f(za.y); eg.x = __builtin_amdgcn_exp2f(zg.x); eg.y = __builtin_amdgcn_exp2f(zg.y);
;                         const f32x2 den = (ea + 1.0f) * (eg + 1.0f);
;                         f32x2 rc; rc.x = __builtin_amdgcn_rcpf(den.x); rc.y = __builtin_amdgcn_rcpf(den.y);
;                         const f32x2 yy = uu * gg * rc;
;                         y[4 * n + 2 * jp] = yy.x; y[4 * n + 2 * jp + 1] = yy.y; }
;                 u32x4 w; w.x = cvt_pk_bf16(y[0], y[1]); w.y = cvt_pk_bf16(y[2], y[3]); w.z = cvt_pk_bf16(y[4], y[5]); w.w = cvt_pk_bf16(y[6], y[7]);
;                 *(u32x4*)rowp = w; }
	s_waitcnt lgkmcnt(0)
	s_setprio 1
	s_waitcnt lgkmcnt(0)
	v_mfma_f32_16x16x32_bf16 v[62:65], v[144:147], v[160:163], v[62:65]
	v_mfma_f32_16x16x32_bf16 v[54:57], v[152:155], v[160:163], v[54:57]
	v_mfma_f32_16x16x32_bf16 v[46:49], v[144:147], v[172:175], v[46:49]
	v_mfma_f32_16x16x32_bf16 v[38:41], v[152:155], v[172:175], v[38:41]
	v_mfma_f32_16x16x32_bf16 v[30:33], v[144:147], v[180:183], v[30:33]
	v_mfma_f32_16x16x32_bf16 v[22:25], v[152:155], v[180:183], v[22:25]
	v_mfma_f32_16x16x32_bf16 v[14:17], v[144:147], v[188:191], v[14:17]
	v_mfma_f32_16x16x32_bf16 v[6:9], v[152:155], v[188:191], v[6:9]
	v_mfma_f32_16x16x32_bf16 v[62:65], v[148:151], v[164:167], v[62:65]
	v_mfma_f32_16x16x32_bf16 v[54:57], v[156:159], v[164:167], v[54:57]
	v_mfma_f32_16x16x32_bf16 v[46:49], v[148:151], v[176:179], v[46:49]
	v_mfma_f32_16x16x32_bf16 v[38:41], v[156:159], v[176:179], v[38:41]
	v_mfma_f32_16x16x32_bf16 v[30:33], v[148:151], v[184:187], v[30:33]
	v_mfma_f32_16x16x32_bf16 v[22:25], v[156:159], v[184:187], v[22:25]
	v_mfma_f32_16x16x32_bf16 v[14:17], v[148:151], v[192:195], v[14:17]
	v_mfma_f32_16x16x32_bf16 v[6:9], v[156:159], v[192:195], v[6:9]
	s_setprio 0
	s_barrier
	s_add_u32 s26, s26, 0x40080
	s_addc_u32 s27, s27, 0
	s_add_i32 s28, s28, s41
	v_lshl_add_u64 v[140:141], s[26:27], 0, v[0:1]
	s_mov_b32 m0, s28
	s_nop 0
	global_load_lds_dwordx4 v[140:141], off
	v_lshl_add_u64 v[140:141], s[26:27], 0, v[130:131]
	s_add_i32 m0, s28, 0x2000
	s_nop 0
	global_load_lds_dwordx4 v[140:141], off
	s_waitcnt vmcnt(6)
	s_barrier
	s_setprio 1
	v_mfma_f32_16x16x32_bf16 v[58:61], v[196:199], v[160:163], v[58:61]
	v_mfma_f32_16x16x32_bf16 v[50:53], v[204:207], v[160:163], v[50:53]
	v_mfma_f32_16x16x32_bf16 v[42:45], v[196:199], v[172:175], v[42:45]
	v_mfma_f32_16x16x32_bf16 v[34:37], v[204:207], v[172:175], v[34:37]
	v_mfma_f32_16x16x32_bf16 v[26:29], v[196:199], v[180:183], v[26:29]
	v_mfma_f32_16x16x32_bf16 v[18:21], v[204:207], v[180:183], v[18:21]
	v_mfma_f32_16x16x32_bf16 v[10:13], v[196:199], v[188:191], v[10:13]
	v_mfma_f32_16x16x32_bf16 v[2:5], v[204:207], v[188:191], v[2:5]
	v_mfma_f32_16x16x32_bf16 v[58:61], v[200:203], v[164:167], v[58:61]
	v_mfma_f32_16x16x32_bf16 v[50:53], v[208:211], v[164:167], v[50:53]
	v_mfma_f32_16x16x32_bf16 v[42:45], v[200:203], v[176:179], v[42:45]
	v_mfma_f32_16x16x32_bf16 v[34:37], v[208:211], v[176:179], v[34:37]
	v_mfma_f32_16x16x32_bf16 v[26:29], v[200:203], v[184:187], v[26:29]
	v_mfma_f32_16x16x32_bf16 v[18:21], v[208:211], v[184:187], v[18:21]
	v_mfma_f32_16x16x32_bf16 v[10:13], v[200:203], v[192:195], v[10:13]
	v_mfma_f32_16x16x32_bf16 v[2:5], v[208:211], v[192:195], v[2:5]
	s_setprio 0
	s_add_i32 s55, s55, 2
	s_add_u32 s24, s24, 0x100
	s_addc_u32 s25, s25, 0
	s_add_u32 s53, s53, 0x100
	s_addc_u32 s54, s54, 0
	s_cmp_gt_u32 s55, 13
	s_barrier
	s_cbranch_scc0 .LBB0_756
	s_mov_b32 s13, s75
	s_mov_b32 s17, s81
	v_pk_mul_f32 v[150:151], v[126:127], v[126:127]
	v_mbcnt_lo_u32_b32 v140, -1, s17
	v_mbcnt_hi_u32_b32 v140, -1, v140
	v_lshl_add_u32 v141, s13, 6, v140
	s_lshl_b32 s13, s22, 8
	s_mov_b32 s22, 0x3d372713
	v_pk_mul_f32 v[148:149], v[128:129], v[128:129]
	v_pk_fma_f32 v[150:151], v[150:151], s[22:23], 1.0 op_sel_hi:[1,0,0]
	v_pk_mul_f32 v[152:153], v[122:123], s[74:75] op_sel_hi:[1,0]
	v_pk_mul_f32 v[150:151], v[126:127], v[150:151]
	v_pk_mul_f32 v[122:123], v[126:127], v[122:123]
	v_pk_fma_f32 v[126:127], v[148:149], s[22:23], 1.0 op_sel_hi:[1,0,0]
	v_pk_mul_f32 v[148:149], v[124:125], s[74:75] op_sel_hi:[1,0]
	v_pk_mul_f32 v[126:127], v[128:129], v[126:127]
	v_exp_f32_e32 v148, v148
	v_pk_mul_f32 v[126:127], v[126:127], s[84:85] op_sel_hi:[1,0]
	v_exp_f32_e32 v149, v149
	v_exp_f32_e32 v126, v126
	v_exp_f32_e32 v127, v127
	v_pk_mul_f32 v[124:125], v[128:129], v[124:125]
	v_pk_mul_f32 v[128:129], v[118:119], v[118:119]
	v_pk_add_f32 v[148:149], v[148:149], 1.0 op_sel_hi:[1,0]
	v_pk_fma_f32 v[128:129], v[128:129], s[22:23], 1.0 op_sel_hi:[1,0,0]
	v_pk_add_f32 v[126:127], v[126:127], 1.0 op_sel_hi:[1,0]
	v_pk_mul_f32 v[128:129], v[118:119], v[128:129]
	v_pk_mul_f32 v[126:127], v[126:127], v[148:149]
	v_pk_mul_f32 v[128:129], v[128:129], s[84:85] op_sel_hi:[1,0]
	v_pk_mul_f32 v[148:149], v[114:115], s[74:75] op_sel_hi:[1,0]
	v_exp_f32_e32 v128, v128
	v_exp_f32_e32 v129, v129
	v_exp_f32_e32 v148, v148
	v_exp_f32_e32 v149, v149
	v_rcp_f32_e32 v126, v126
	v_pk_add_f32 v[128:129], v[128:129], 1.0 op_sel_hi:[1,0]
	v_rcp_f32_e32 v127, v127
	v_pk_add_f32 v[148:149], v[148:149], 1.0 op_sel_hi:[1,0]
	v_pk_mul_f32 v[114:115], v[118:119], v[114:115]
	v_pk_mul_f32 v[128:129], v[128:129], v[148:149]
	v_pk_mul_f32 v[124:125], v[124:125], v[126:127]
	v_rcp_f32_e32 v128, v128
	v_rcp_f32_e32 v129, v129
	v_pk_mul_f32 v[126:127], v[120:121], v[120:121]
	v_pk_mul_f32 v[150:151], v[150:151], s[84:85] op_sel_hi:[1,0]
	v_pk_mul_f32 v[118:119], v[116:117], s[74:75] op_sel_hi:[1,0]
	v_pk_mul_f32 v[128:129], v[114:115], v[128:129]
	v_pk_fma_f32 v[114:115], v[126:127], s[22:23], 1.0 op_sel_hi:[1,0,0]
	v_exp_f32_e32 v150, v150
	v_pk_mul_f32 v[114:115], v[120:121], v[114:115]
	v_exp_f32_e32 v151, v151
	v_pk_mul_f32 v[114:115], v[114:115], s[84:85] op_sel_hi:[1,0]
	v_exp_f32_e32 v152, v152
	v_exp_f32_e32 v153, v153
	v_exp_f32_e32 v114, v114
	v_exp_f32_e32 v115, v115
	v_exp_f32_e32 v118, v118
	v_exp_f32_e32 v119, v119
	v_pk_add_f32 v[150:151], v[150:151], 1.0 op_sel_hi:[1,0]
	v_pk_add_f32 v[152:153], v[152:153], 1.0 op_sel_hi:[1,0]
	v_pk_add_f32 v[114:115], v[114:115], 1.0 op_sel_hi:[1,0]
	v_pk_add_f32 v[118:119], v[118:119], 1.0 op_sel_hi:[1,0]
	v_mov_b32_e32 v140, s13
	v_and_b32_e32 v141, 63, v141
	v_pk_mul_f32 v[150:151], v[150:151], v[152:153]
; __device__ __forceinline__ unsigned cvt_pk_bf16(float lo, float hi) { unsigned r; asm volatile("v_cvt_pk_bf16_f32 %0, %1, %2" : "=v"(r) : "v"(lo), "v"(hi)); return r; }
;     EPI_ZERO_INIT
;     __device__ __forceinline__ void operator()(AccRef acc, const Unit& u, int sw) const {
;     ...
;             for (int m = 0; m < 4; ++m) { bf16_t* rowp = UG + (size_t)(row0 + ai * HALF + m * 16) * E + c0;
;                 float y[8];
; #pragma unroll
;                 for (int n = 0; n < 2; ++n)
; #pragma unroll
;                     for (int jp = 0; jp < 2; ++jp) {
;                         const f32x2 uu = (f32x2){acc[ai][0][m][n][2 * jp], acc[ai][0][m][n][2 * jp + 1]}, gg = (f32x2){acc[ai][1][m][n][2 * jp], acc[ai][1][m][n][2 * jp + 1]};
;                         const f32x2 za = (uu * uu * 0.044715f + 1.0f) * uu * (-1.44269504f * 1.59576912f), zg = gg * (-1.44269504f);
;                         f32x2 ea, eg; ea.x = __builtin_amdgcn_exp2f(za.x); ea.y = __builtin_amdgcn_exp2f(za.y); eg.x = __builtin_amdgcn_exp2f(zg.x); eg.y = __builtin_amdgcn_exp2f(zg.y);
;                         const f32x2 den = (ea + 1.0f) * (eg + 1.0f);
;                         f32x2 rc; rc.x = __builtin_amdgcn_rcpf(den.x); rc.y = __builtin_amdgcn_rcpf(den.y);
;                         const f32x2 yy = uu * gg * rc;
;                         y[4 * n + 2 * jp] = yy.x; y[4 * n + 2 * jp + 1] = yy.y; }
;                 u32x4 w; w.x = cvt_pk_bf16(y[0], y[1]); w.y = cvt_pk_bf16(y[2], y[3]); w.z = cvt_pk_bf16(y[4], y[5]); w.w = cvt_pk_bf16(y[6], y[7]);
;                 *(u32x4*)rowp = w; }
	v_pk_mul_f32 v[114:115], v[114:115], v[118:119]
	v_lshlrev_b32_e32 v141, 3, v141
	v_rcp_f32_e32 v150, v150
	v_rcp_f32_e32 v151, v151
	v_rcp_f32_e32 v114, v114
	v_rcp_f32_e32 v115, v115
	v_lshl_or_b32 v141, s50, 14, v141
	v_lshl_or_b32 v144, s85, 7, v141
	v_lshl_or_b32 v144, s3, 5, v144
	v_ashrrev_i32_e32 v141, 31, v140
	v_ashrrev_i32_e32 v145, 31, v144
	v_lshlrev_b64 v[146:147], 12, v[140:141]
	v_pk_mul_f32 v[116:117], v[120:121], v[116:117]
	v_lshl_add_u64 v[146:147], s[10:11], 0, v[146:147]
	v_pk_mul_f32 v[122:123], v[122:123], v[150:151]
	v_pk_mul_f32 v[126:127], v[116:117], v[114:115]
	v_lshlrev_b64 v[116:117], 1, v[144:145]
	v_lshl_add_u64 v[114:115], v[146:147], 0, v[116:117]
	v_cvt_pk_bf16_f32 v118, v122, v123
	v_cvt_pk_bf16_f32 v119, v124, v125
	v_cvt_pk_bf16_f32 v120, v128, v129
	v_cvt_pk_bf16_f32 v121, v126, v127
	v_pk_mul_f32 v[122:123], v[110:111], v[110:111]
	global_store_dwordx4 v[114:115], v[118:121], off
	v_pk_fma_f32 v[122:123], v[122:123], s[22:23], 1.0 op_sel_hi:[1,0,0]
	v_pk_mul_f32 v[124:125], v[106:107], s[74:75] op_sel_hi:[1,0]
	v_pk_mul_f32 v[120:121], v[112:113], v[112:113]
	v_pk_mul_f32 v[122:123], v[110:111], v[122:123]
	v_pk_mul_f32 v[106:107], v[110:111], v[106:107]
	v_pk_fma_f32 v[110:111], v[120:121], s[22:23], 1.0 op_sel_hi:[1,0,0]
	v_pk_mul_f32 v[120:121], v[108:109], s[74:75] op_sel_hi:[1,0]
	v_pk_mul_f32 v[110:111], v[112:113], v[110:111]
	v_exp_f32_e32 v120, v120
	v_pk_mul_f32 v[110:111], v[110:111], s[84:85] op_sel_hi:[1,0]
	v_exp_f32_e32 v121, v121
	v_exp_f32_e32 v110, v110
	v_exp_f32_e32 v111, v111
	v_pk_mul_f32 v[108:109], v[112:113], v[108:109]
	v_pk_mul_f32 v[112:113], v[102:103], v[102:103]
	v_pk_add_f32 v[120:121], v[120:121], 1.0 op_sel_hi:[1,0]
	v_pk_fma_f32 v[112:113], v[112:113], s[22:23], 1.0 op_sel_hi:[1,0,0]
	v_pk_add_f32 v[110:111], v[110:111], 1.0 op_sel_hi:[1,0]
	v_pk_mul_f32 v[112:113], v[102:103], v[112:113]
	v_pk_mul_f32 v[110:111], v[110:111], v[120:121]
	v_pk_mul_f32 v[112:113], v[112:113], s[84:85] op_sel_hi:[1,0]
	v_pk_mul_f32 v[120:121], v[98:99], s[74:75] op_sel_hi:[1,0]
	v_exp_f32_e32 v112, v112
	v_exp_f32_e32 v113, v113
	v_exp_f32_e32 v120, v120
	v_exp_f32_e32 v121, v121
	v_rcp_f32_e32 v110, v110
	v_pk_add_f32 v[112:113], v[112:113], 1.0 op_sel_hi:[1,0]
	v_rcp_f32_e32 v111, v111
	v_pk_add_f32 v[120:121], v[120:121], 1.0 op_sel_hi:[1,0]
	v_pk_mul_f32 v[98:99], v[102:103], v[98:99]
	v_pk_mul_f32 v[112:113], v[112:113], v[120:121]
	v_pk_mul_f32 v[108:109], v[108:109], v[110:111]
	v_rcp_f32_e32 v112, v112
	v_rcp_f32_e32 v113, v113
	v_pk_mul_f32 v[110:111], v[104:105], v[104:105]
	v_pk_mul_f32 v[122:123], v[122:123], s[84:85] op_sel_hi:[1,0]
	v_exp_f32_e32 v124, v124
	v_pk_mul_f32 v[102:103], v[98:99], v[112:113]
	v_pk_fma_f32 v[98:99], v[110:111], s[22:23], 1.0 op_sel_hi:[1,0,0]
	v_pk_mul_f32 v[110:111], v[100:101], s[74:75] op_sel_hi:[1,0]
	v_pk_mul_f32 v[98:99], v[104:105], v[98:99]
	v_exp_f32_e32 v122, v122
	v_pk_mul_f32 v[98:99], v[98:99], s[84:85] op_sel_hi:[1,0]
	v_exp_f32_e32 v123, v123
	v_exp_f32_e32 v125, v125
	v_exp_f32_e32 v98, v98
	v_exp_f32_e32 v99, v99
	v_exp_f32_e32 v110, v110
	v_exp_f32_e32 v111, v111
	v_pk_add_f32 v[122:123], v[122:123], 1.0 op_sel_hi:[1,0]
	v_pk_add_f32 v[124:125], v[124:125], 1.0 op_sel_hi:[1,0]
	v_pk_add_f32 v[98:99], v[98:99], 1.0 op_sel_hi:[1,0]
	v_pk_add_f32 v[110:111], v[110:111], 1.0 op_sel_hi:[1,0]
	v_pk_mul_f32 v[122:123], v[122:123], v[124:125]
	v_pk_mul_f32 v[98:99], v[98:99], v[110:111]
	v_or_b32_e32 v118, 16, v140
	v_rcp_f32_e32 v122, v122
	v_rcp_f32_e32 v123, v123
	v_rcp_f32_e32 v98, v98
	v_rcp_f32_e32 v99, v99
	v_ashrrev_i32_e32 v119, 31, v118
	v_lshlrev_b64 v[118:119], 12, v[118:119]
	v_lshl_add_u64 v[118:119], s[10:11], 0, v[118:119]
	v_pk_mul_f32 v[100:101], v[104:105], v[100:101]
	v_pk_mul_f32 v[106:107], v[106:107], v[122:123]
	v_pk_mul_f32 v[104:105], v[100:101], v[98:99]
	v_lshl_add_u64 v[110:111], v[118:119], 0, v[116:117]
	v_cvt_pk_bf16_f32 v98, v106, v107
	v_cvt_pk_bf16_f32 v99, v108, v109
	v_cvt_pk_bf16_f32 v100, v102, v103
	v_cvt_pk_bf16_f32 v101, v104, v105
	v_pk_mul_f32 v[102:103], v[94:95], v[94:95]
	global_store_dwordx4 v[114:115], v[98:101], off offset:1024
	v_pk_fma_f32 v[102:103], v[102:103], s[22:23], 1.0 op_sel_hi:[1,0,0]
	v_pk_mul_f32 v[104:105], v[90:91], s[74:75] op_sel_hi:[1,0]
	v_pk_mul_f32 v[100:101], v[96:97], v[96:97]
	v_pk_mul_f32 v[102:103], v[94:95], v[102:103]
	v_pk_mul_f32 v[90:91], v[94:95], v[90:91]
	v_pk_fma_f32 v[94:95], v[100:101], s[22:23], 1.0 op_sel_hi:[1,0,0]
	v_pk_mul_f32 v[100:101], v[92:93], s[74:75] op_sel_hi:[1,0]
	v_pk_mul_f32 v[94:95], v[96:97], v[94:95]
	v_exp_f32_e32 v100, v100
	v_pk_mul_f32 v[94:95], v[94:95], s[84:85] op_sel_hi:[1,0]
	v_exp_f32_e32 v101, v101
	v_exp_f32_e32 v94, v94
	v_exp_f32_e32 v95, v95
	v_pk_mul_f32 v[92:93], v[96:97], v[92:93]
	v_pk_mul_f32 v[96:97], v[86:87], v[86:87]
	v_pk_add_f32 v[100:101], v[100:101], 1.0 op_sel_hi:[1,0]
	v_pk_fma_f32 v[96:97], v[96:97], s[22:23], 1.0 op_sel_hi:[1,0,0]
	v_pk_add_f32 v[94:95], v[94:95], 1.0 op_sel_hi:[1,0]
	v_pk_mul_f32 v[96:97], v[86:87], v[96:97]
	v_pk_mul_f32 v[94:95], v[94:95], v[100:101]
	v_pk_mul_f32 v[96:97], v[96:97], s[84:85] op_sel_hi:[1,0]
	v_pk_mul_f32 v[100:101], v[82:83], s[74:75] op_sel_hi:[1,0]
	v_exp_f32_e32 v96, v96
	v_exp_f32_e32 v97, v97
	v_exp_f32_e32 v100, v100
	v_exp_f32_e32 v101, v101
	v_rcp_f32_e32 v94, v94
	v_pk_add_f32 v[96:97], v[96:97], 1.0 op_sel_hi:[1,0]
	v_rcp_f32_e32 v95, v95
	v_pk_add_f32 v[100:101], v[100:101], 1.0 op_sel_hi:[1,0]
	v_pk_mul_f32 v[82:83], v[86:87], v[82:83]
	v_pk_mul_f32 v[96:97], v[96:97], v[100:101]
	v_pk_mul_f32 v[92:93], v[92:93], v[94:95]
	v_rcp_f32_e32 v96, v96
; __device__ __forceinline__ unsigned cvt_pk_bf16(float lo, float hi) { unsigned r; asm volatile("v_cvt_pk_bf16_f32 %0, %1, %2" : "=v"(r) : "v"(lo), "v"(hi)); return r; }
;     EPI_ZERO_INIT
;     __device__ __forceinline__ void operator()(AccRef acc, const Unit& u, int sw) const {
;     ...
;             for (int m = 0; m < 4; ++m) { bf16_t* rowp = UG + (size_t)(row0 + ai * HALF + m * 16) * E + c0;
;                 float y[8];
; #pragma unroll
;                 for (int n = 0; n < 2; ++n)
; #pragma unroll
;                     for (int jp = 0; jp < 2; ++jp) {
;                         const f32x2 uu = (f32x2){acc[ai][0][m][n][2 * jp], acc[ai][0][m][n][2 * jp + 1]}, gg = (f32x2){acc[ai][1][m][n][2 * jp], acc[ai][1][m][n][2 * jp + 1]};
;                         const f32x2 za = (uu * uu * 0.044715f + 1.0f) * uu * (-1.44269504f * 1.59576912f), zg = gg * (-1.44269504f);
;                         f32x2 ea, eg; ea.x = __builtin_amdgcn_exp2f(za.x); ea.y = __builtin_amdgcn_exp2f(za.y); eg.x = __builtin_amdgcn_exp2f(zg.x); eg.y = __builtin_amdgcn_exp2f(zg.y);
;                         const f32x2 den = (ea + 1.0f) * (eg + 1.0f);
;                         f32x2 rc; rc.x = __builtin_amdgcn_rcpf(den.x); rc.y = __builtin_amdgcn_rcpf(den.y);
;                         const f32x2 yy = uu * gg * rc;
;                         y[4 * n + 2 * jp] = yy.x; y[4 * n + 2 * jp + 1] = yy.y; }
;                 u32x4 w; w.x = cvt_pk_bf16(y[0], y[1]); w.y = cvt_pk_bf16(y[2], y[3]); w.z = cvt_pk_bf16(y[4], y[5]); w.w = cvt_pk_bf16(y[6], y[7]);
;                 *(u32x4*)rowp = w; }
	v_rcp_f32_e32 v97, v97
	v_pk_mul_f32 v[94:95], v[88:89], v[88:89]
	v_pk_mul_f32 v[102:103], v[102:103], s[84:85] op_sel_hi:[1,0]
	v_exp_f32_e32 v104, v104
	v_pk_mul_f32 v[86:87], v[82:83], v[96:97]
	v_pk_fma_f32 v[82:83], v[94:95], s[22:23], 1.0 op_sel_hi:[1,0,0]
	v_pk_mul_f32 v[94:95], v[84:85], s[74:75] op_sel_hi:[1,0]
	v_pk_mul_f32 v[82:83], v[88:89], v[82:83]
	v_exp_f32_e32 v102, v102
	v_pk_mul_f32 v[82:83], v[82:83], s[84:85] op_sel_hi:[1,0]
	v_exp_f32_e32 v103, v103
	v_exp_f32_e32 v105, v105
	v_exp_f32_e32 v82, v82
	v_exp_f32_e32 v83, v83
	v_exp_f32_e32 v94, v94
	v_exp_f32_e32 v95, v95
	v_pk_add_f32 v[102:103], v[102:103], 1.0 op_sel_hi:[1,0]
	v_pk_add_f32 v[104:105], v[104:105], 1.0 op_sel_hi:[1,0]
	v_pk_add_f32 v[82:83], v[82:83], 1.0 op_sel_hi:[1,0]
	v_pk_add_f32 v[94:95], v[94:95], 1.0 op_sel_hi:[1,0]
	v_pk_mul_f32 v[102:103], v[102:103], v[104:105]
	v_pk_mul_f32 v[82:83], v[82:83], v[94:95]
	v_or_b32_e32 v98, 32, v140
	v_rcp_f32_e32 v102, v102
	v_rcp_f32_e32 v103, v103
	v_rcp_f32_e32 v82, v82
	v_rcp_f32_e32 v83, v83
	v_ashrrev_i32_e32 v99, 31, v98
	v_lshlrev_b64 v[98:99], 12, v[98:99]
	v_lshl_add_u64 v[98:99], s[10:11], 0, v[98:99]
	v_pk_mul_f32 v[84:85], v[88:89], v[84:85]
	v_pk_mul_f32 v[90:91], v[90:91], v[102:103]
	v_pk_mul_f32 v[88:89], v[84:85], v[82:83]
	v_lshl_add_u64 v[94:95], v[98:99], 0, v[116:117]
	v_cvt_pk_bf16_f32 v82, v90, v91
	v_cvt_pk_bf16_f32 v83, v92, v93
	v_cvt_pk_bf16_f32 v84, v86, v87
	v_cvt_pk_bf16_f32 v85, v88, v89
	v_pk_mul_f32 v[86:87], v[78:79], v[78:79]
	global_store_dwordx4 v[114:115], v[82:85], off offset:2048
	v_pk_fma_f32 v[86:87], v[86:87], s[22:23], 1.0 op_sel_hi:[1,0,0]
	v_pk_mul_f32 v[88:89], v[74:75], s[74:75] op_sel_hi:[1,0]
	v_pk_mul_f32 v[84:85], v[80:81], v[80:81]
	v_pk_mul_f32 v[86:87], v[78:79], v[86:87]
	v_pk_mul_f32 v[74:75], v[78:79], v[74:75]
	v_pk_fma_f32 v[78:79], v[84:85], s[22:23], 1.0 op_sel_hi:[1,0,0]
	v_pk_mul_f32 v[84:85], v[76:77], s[74:75] op_sel_hi:[1,0]
	v_pk_mul_f32 v[78:79], v[80:81], v[78:79]
	v_exp_f32_e32 v84, v84
	v_pk_mul_f32 v[78:79], v[78:79], s[84:85] op_sel_hi:[1,0]
	v_exp_f32_e32 v85, v85
	v_exp_f32_e32 v78, v78
	v_exp_f32_e32 v79, v79
	v_pk_mul_f32 v[76:77], v[80:81], v[76:77]
	v_pk_mul_f32 v[80:81], v[70:71], v[70:71]
	v_pk_add_f32 v[84:85], v[84:85], 1.0 op_sel_hi:[1,0]
	v_pk_fma_f32 v[80:81], v[80:81], s[22:23], 1.0 op_sel_hi:[1,0,0]
	v_pk_add_f32 v[78:79], v[78:79], 1.0 op_sel_hi:[1,0]
	v_pk_mul_f32 v[80:81], v[70:71], v[80:81]
	v_pk_mul_f32 v[78:79], v[78:79], v[84:85]
	v_pk_mul_f32 v[80:81], v[80:81], s[84:85] op_sel_hi:[1,0]
	v_pk_mul_f32 v[84:85], v[66:67], s[74:75] op_sel_hi:[1,0]
	v_exp_f32_e32 v80, v80
	v_exp_f32_e32 v81, v81
	v_exp_f32_e32 v84, v84
	v_exp_f32_e32 v85, v85
	v_rcp_f32_e32 v78, v78
	v_pk_add_f32 v[80:81], v[80:81], 1.0 op_sel_hi:[1,0]
	v_rcp_f32_e32 v79, v79
	v_pk_add_f32 v[84:85], v[84:85], 1.0 op_sel_hi:[1,0]
	v_pk_mul_f32 v[66:67], v[70:71], v[66:67]
	v_pk_mul_f32 v[80:81], v[80:81], v[84:85]
	v_pk_mul_f32 v[76:77], v[76:77], v[78:79]
	v_rcp_f32_e32 v80, v80
	v_rcp_f32_e32 v81, v81
	v_pk_mul_f32 v[78:79], v[72:73], v[72:73]
	v_pk_mul_f32 v[86:87], v[86:87], s[84:85] op_sel_hi:[1,0]
	v_exp_f32_e32 v88, v88
	v_pk_mul_f32 v[70:71], v[66:67], v[80:81]
	v_pk_fma_f32 v[66:67], v[78:79], s[22:23], 1.0 op_sel_hi:[1,0,0]
	v_pk_mul_f32 v[78:79], v[68:69], s[74:75] op_sel_hi:[1,0]
	v_pk_mul_f32 v[66:67], v[72:73], v[66:67]
	v_exp_f32_e32 v86, v86
	v_pk_mul_f32 v[66:67], v[66:67], s[84:85] op_sel_hi:[1,0]
	v_exp_f32_e32 v87, v87
	v_exp_f32_e32 v89, v89
	v_exp_f32_e32 v66, v66
	v_exp_f32_e32 v67, v67
	v_exp_f32_e32 v78, v78
	v_exp_f32_e32 v79, v79
	v_pk_add_f32 v[86:87], v[86:87], 1.0 op_sel_hi:[1,0]
	v_pk_add_f32 v[88:89], v[88:89], 1.0 op_sel_hi:[1,0]
	v_pk_add_f32 v[66:67], v[66:67], 1.0 op_sel_hi:[1,0]
	v_pk_add_f32 v[78:79], v[78:79], 1.0 op_sel_hi:[1,0]
	v_pk_mul_f32 v[86:87], v[86:87], v[88:89]
	v_pk_mul_f32 v[66:67], v[66:67], v[78:79]
	v_or_b32_e32 v82, 48, v140
	v_rcp_f32_e32 v86, v86
	v_rcp_f32_e32 v87, v87
	v_rcp_f32_e32 v66, v66
	v_rcp_f32_e32 v67, v67
	v_ashrrev_i32_e32 v83, 31, v82
	v_lshlrev_b64 v[82:83], 12, v[82:83]
	v_lshl_add_u64 v[82:83], s[10:11], 0, v[82:83]
	v_pk_mul_f32 v[68:69], v[72:73], v[68:69]
	v_pk_mul_f32 v[74:75], v[74:75], v[86:87]
	v_pk_mul_f32 v[72:73], v[68:69], v[66:67]
	v_lshl_add_u64 v[78:79], v[82:83], 0, v[116:117]
	v_cvt_pk_bf16_f32 v66, v74, v75
	v_cvt_pk_bf16_f32 v67, v76, v77
	v_cvt_pk_bf16_f32 v68, v70, v71
	v_cvt_pk_bf16_f32 v69, v72, v73
	global_store_dwordx4 v[114:115], v[66:69], off offset:3072
	v_pk_mul_f32 v[70:71], v[58:59], s[74:75] op_sel_hi:[1,0]
	v_pk_mul_f32 v[58:59], v[62:63], v[58:59]
	v_pk_mul_f32 v[68:69], v[62:63], v[62:63]
	v_pk_mul_f32 v[66:67], v[64:65], v[64:65]
	v_pk_fma_f32 v[68:69], v[68:69], s[22:23], 1.0 op_sel_hi:[1,0,0]
	v_exp_f32_e32 v70, v70
	v_pk_mul_f32 v[68:69], v[62:63], v[68:69]
	v_pk_fma_f32 v[62:63], v[66:67], s[22:23], 1.0 op_sel_hi:[1,0,0]
	v_pk_mul_f32 v[66:67], v[60:61], s[74:75] op_sel_hi:[1,0]
	v_pk_mul_f32 v[62:63], v[64:65], v[62:63]
	v_exp_f32_e32 v66, v66
	v_pk_mul_f32 v[62:63], v[62:63], s[84:85] op_sel_hi:[1,0]
	v_exp_f32_e32 v67, v67
	v_exp_f32_e32 v62, v62
	v_exp_f32_e32 v63, v63
	v_pk_mul_f32 v[60:61], v[64:65], v[60:61]
	v_pk_mul_f32 v[64:65], v[54:55], v[54:55]
	v_pk_add_f32 v[66:67], v[66:67], 1.0 op_sel_hi:[1,0]
	v_pk_fma_f32 v[64:65], v[64:65], s[22:23], 1.0 op_sel_hi:[1,0,0]
	v_pk_add_f32 v[62:63], v[62:63], 1.0 op_sel_hi:[1,0]
	v_pk_mul_f32 v[64:65], v[54:55], v[64:65]
	v_pk_mul_f32 v[62:63], v[62:63], v[66:67]
	v_pk_mul_f32 v[64:65], v[64:65], s[84:85] op_sel_hi:[1,0]
	v_pk_mul_f32 v[66:67], v[50:51], s[74:75] op_sel_hi:[1,0]
; __device__ __forceinline__ unsigned cvt_pk_bf16(float lo, float hi) { unsigned r; asm volatile("v_cvt_pk_bf16_f32 %0, %1, %2" : "=v"(r) : "v"(lo), "v"(hi)); return r; }
;     EPI_ZERO_INIT
;     __device__ __forceinline__ void operator()(AccRef acc, const Unit& u, int sw) const {
;     ...
;             for (int m = 0; m < 4; ++m) { bf16_t* rowp = UG + (size_t)(row0 + ai * HALF + m * 16) * E + c0;
;                 float y[8];
; #pragma unroll
;                 for (int n = 0; n < 2; ++n)
; #pragma unroll
;                     for (int jp = 0; jp < 2; ++jp) {
;                         const f32x2 uu = (f32x2){acc[ai][0][m][n][2 * jp], acc[ai][0][m][n][2 * jp + 1]}, gg = (f32x2){acc[ai][1][m][n][2 * jp], acc[ai][1][m][n][2 * jp + 1]};
;                         const f32x2 za = (uu * uu * 0.044715f + 1.0f) * uu * (-1.44269504f * 1.59576912f), zg = gg * (-1.44269504f);
;                         f32x2 ea, eg; ea.x = __builtin_amdgcn_exp2f(za.x); ea.y = __builtin_amdgcn_exp2f(za.y); eg.x = __builtin_amdgcn_exp2f(zg.x); eg.y = __builtin_amdgcn_exp2f(zg.y);
;                         const f32x2 den = (ea + 1.0f) * (eg + 1.0f);
;                         f32x2 rc; rc.x = __builtin_amdgcn_rcpf(den.x); rc.y = __builtin_amdgcn_rcpf(den.y);
;                         const f32x2 yy = uu * gg * rc;
;                         y[4 * n + 2 * jp] = yy.x; y[4 * n + 2 * jp + 1] = yy.y; }
;                 u32x4 w; w.x = cvt_pk_bf16(y[0], y[1]); w.y = cvt_pk_bf16(y[2], y[3]); w.z = cvt_pk_bf16(y[4], y[5]); w.w = cvt_pk_bf16(y[6], y[7]);
;                 *(u32x4*)rowp = w; }
	v_exp_f32_e32 v64, v64
	v_exp_f32_e32 v65, v65
	v_exp_f32_e32 v66, v66
	v_exp_f32_e32 v67, v67
	v_rcp_f32_e32 v62, v62
	v_pk_add_f32 v[64:65], v[64:65], 1.0 op_sel_hi:[1,0]
	v_rcp_f32_e32 v63, v63
	v_pk_add_f32 v[66:67], v[66:67], 1.0 op_sel_hi:[1,0]
	v_pk_mul_f32 v[50:51], v[54:55], v[50:51]
	v_pk_mul_f32 v[64:65], v[64:65], v[66:67]
	v_pk_mul_f32 v[60:61], v[60:61], v[62:63]
	v_rcp_f32_e32 v64, v64
	v_rcp_f32_e32 v65, v65
	v_pk_mul_f32 v[62:63], v[56:57], v[56:57]
	v_pk_mul_f32 v[68:69], v[68:69], s[84:85] op_sel_hi:[1,0]
	v_exp_f32_e32 v71, v71
	v_pk_mul_f32 v[54:55], v[50:51], v[64:65]
	v_pk_fma_f32 v[50:51], v[62:63], s[22:23], 1.0 op_sel_hi:[1,0,0]
	v_pk_mul_f32 v[62:63], v[52:53], s[74:75] op_sel_hi:[1,0]
	v_pk_mul_f32 v[50:51], v[56:57], v[50:51]
	v_exp_f32_e32 v68, v68
	v_pk_mul_f32 v[50:51], v[50:51], s[84:85] op_sel_hi:[1,0]
	v_exp_f32_e32 v69, v69
	v_exp_f32_e32 v50, v50
	v_exp_f32_e32 v51, v51
	v_exp_f32_e32 v62, v62
	v_exp_f32_e32 v63, v63
	v_pk_add_f32 v[68:69], v[68:69], 1.0 op_sel_hi:[1,0]
	v_pk_add_f32 v[70:71], v[70:71], 1.0 op_sel_hi:[1,0]
	v_pk_add_f32 v[50:51], v[50:51], 1.0 op_sel_hi:[1,0]
	v_pk_add_f32 v[62:63], v[62:63], 1.0 op_sel_hi:[1,0]
	v_pk_mul_f32 v[68:69], v[68:69], v[70:71]
	v_pk_mul_f32 v[50:51], v[50:51], v[62:63]
	v_rcp_f32_e32 v68, v68
	v_rcp_f32_e32 v69, v69
	v_rcp_f32_e32 v50, v50
	v_rcp_f32_e32 v51, v51
	v_pk_mul_f32 v[52:53], v[56:57], v[52:53]
	s_mov_b32 s13, 0x80000
	v_pk_mul_f32 v[58:59], v[58:59], v[68:69]
	v_pk_mul_f32 v[56:57], v[52:53], v[50:51]
	v_cvt_pk_bf16_f32 v50, v58, v59
	v_cvt_pk_bf16_f32 v51, v60, v61
	v_cvt_pk_bf16_f32 v52, v54, v55
	v_add_co_u32_e32 v54, vcc, s13, v114
	v_cvt_pk_bf16_f32 v53, v56, v57
	s_mov_b32 s13, 0x80400
	s_nop 0
	v_addc_co_u32_e32 v55, vcc, 0, v115, vcc
	global_store_dwordx4 v[54:55], v[50:53], off
	v_pk_mul_f32 v[54:55], v[42:43], s[74:75] op_sel_hi:[1,0]
	v_pk_mul_f32 v[42:43], v[46:47], v[42:43]
	v_pk_mul_f32 v[52:53], v[46:47], v[46:47]
	v_pk_mul_f32 v[50:51], v[48:49], v[48:49]
	v_pk_fma_f32 v[52:53], v[52:53], s[22:23], 1.0 op_sel_hi:[1,0,0]
	v_exp_f32_e32 v54, v54
	v_pk_mul_f32 v[52:53], v[46:47], v[52:53]
	v_pk_fma_f32 v[46:47], v[50:51], s[22:23], 1.0 op_sel_hi:[1,0,0]
	v_pk_mul_f32 v[50:51], v[44:45], s[74:75] op_sel_hi:[1,0]
	v_pk_mul_f32 v[46:47], v[48:49], v[46:47]
	v_exp_f32_e32 v50, v50
	v_pk_mul_f32 v[46:47], v[46:47], s[84:85] op_sel_hi:[1,0]
	v_exp_f32_e32 v51, v51
	v_exp_f32_e32 v46, v46
	v_exp_f32_e32 v47, v47
	v_pk_mul_f32 v[44:45], v[48:49], v[44:45]
	v_pk_mul_f32 v[48:49], v[38:39], v[38:39]
	v_pk_add_f32 v[50:51], v[50:51], 1.0 op_sel_hi:[1,0]
	v_pk_fma_f32 v[48:49], v[48:49], s[22:23], 1.0 op_sel_hi:[1,0,0]
	v_pk_add_f32 v[46:47], v[46:47], 1.0 op_sel_hi:[1,0]
	v_pk_mul_f32 v[48:49], v[38:39], v[48:49]
	v_pk_mul_f32 v[46:47], v[46:47], v[50:51]
	v_pk_mul_f32 v[48:49], v[48:49], s[84:85] op_sel_hi:[1,0]
	v_pk_mul_f32 v[50:51], v[34:35], s[74:75] op_sel_hi:[1,0]
	v_exp_f32_e32 v48, v48
	v_exp_f32_e32 v49, v49
	v_exp_f32_e32 v50, v50
	v_exp_f32_e32 v51, v51
	v_rcp_f32_e32 v46, v46
	v_pk_add_f32 v[48:49], v[48:49], 1.0 op_sel_hi:[1,0]
	v_rcp_f32_e32 v47, v47
	v_pk_add_f32 v[50:51], v[50:51], 1.0 op_sel_hi:[1,0]
	v_pk_mul_f32 v[34:35], v[38:39], v[34:35]
	v_pk_mul_f32 v[48:49], v[48:49], v[50:51]
	v_pk_mul_f32 v[44:45], v[44:45], v[46:47]
	v_rcp_f32_e32 v48, v48
	v_rcp_f32_e32 v49, v49
	v_pk_mul_f32 v[46:47], v[40:41], v[40:41]
	v_pk_mul_f32 v[52:53], v[52:53], s[84:85] op_sel_hi:[1,0]
	v_exp_f32_e32 v55, v55
	v_pk_mul_f32 v[38:39], v[34:35], v[48:49]
	v_pk_fma_f32 v[34:35], v[46:47], s[22:23], 1.0 op_sel_hi:[1,0,0]
	v_pk_mul_f32 v[46:47], v[36:37], s[74:75] op_sel_hi:[1,0]
	v_pk_mul_f32 v[34:35], v[40:41], v[34:35]
	v_exp_f32_e32 v52, v52
	v_pk_mul_f32 v[34:35], v[34:35], s[84:85] op_sel_hi:[1,0]
	v_exp_f32_e32 v53, v53
	v_exp_f32_e32 v34, v34
	v_exp_f32_e32 v35, v35
	v_exp_f32_e32 v46, v46
	v_exp_f32_e32 v47, v47
	v_pk_add_f32 v[52:53], v[52:53], 1.0 op_sel_hi:[1,0]
	v_pk_add_f32 v[54:55], v[54:55], 1.0 op_sel_hi:[1,0]
	v_pk_add_f32 v[34:35], v[34:35], 1.0 op_sel_hi:[1,0]
	v_pk_add_f32 v[46:47], v[46:47], 1.0 op_sel_hi:[1,0]
	v_pk_mul_f32 v[52:53], v[52:53], v[54:55]
	v_pk_mul_f32 v[34:35], v[34:35], v[46:47]
	v_rcp_f32_e32 v52, v52
	v_rcp_f32_e32 v53, v53
	v_rcp_f32_e32 v34, v34
	v_rcp_f32_e32 v35, v35
	v_pk_mul_f32 v[36:37], v[40:41], v[36:37]
	v_pk_mul_f32 v[42:43], v[42:43], v[52:53]
	v_pk_mul_f32 v[40:41], v[36:37], v[34:35]
	v_cvt_pk_bf16_f32 v34, v42, v43
	v_cvt_pk_bf16_f32 v35, v44, v45
	v_cvt_pk_bf16_f32 v36, v38, v39
	v_add_co_u32_e32 v38, vcc, s13, v114
	v_cvt_pk_bf16_f32 v37, v40, v41
	s_mov_b32 s13, 0x80800
	s_nop 0
	v_addc_co_u32_e32 v39, vcc, 0, v115, vcc
	global_store_dwordx4 v[38:39], v[34:37], off
	v_pk_mul_f32 v[38:39], v[26:27], s[74:75] op_sel_hi:[1,0]
	v_pk_mul_f32 v[26:27], v[30:31], v[26:27]
	v_pk_mul_f32 v[36:37], v[30:31], v[30:31]
	v_pk_mul_f32 v[34:35], v[32:33], v[32:33]
	v_pk_fma_f32 v[36:37], v[36:37], s[22:23], 1.0 op_sel_hi:[1,0,0]
	v_exp_f32_e32 v38, v38
	v_pk_mul_f32 v[36:37], v[30:31], v[36:37]
	v_pk_fma_f32 v[30:31], v[34:35], s[22:23], 1.0 op_sel_hi:[1,0,0]
	v_pk_mul_f32 v[34:35], v[28:29], s[74:75] op_sel_hi:[1,0]
	v_pk_mul_f32 v[30:31], v[32:33], v[30:31]
	v_exp_f32_e32 v34, v34
	v_pk_mul_f32 v[30:31], v[30:31], s[84:85] op_sel_hi:[1,0]
	v_exp_f32_e32 v35, v35
; __device__ __forceinline__ unsigned cvt_pk_bf16(float lo, float hi) { unsigned r; asm volatile("v_cvt_pk_bf16_f32 %0, %1, %2" : "=v"(r) : "v"(lo), "v"(hi)); return r; }
; template <class Epi>
; __device__ __forceinline__ void gemm_phase(LAS unsigned char* lds, const Gemm g, const StaticOrder& S_in, const Epi& E, int sw) {
;     ...
;         if (!has_next) break;
;         E.init(acc, nxt, sw);
;         cur = nxt; cA = nA; cB = nB; ++ui;
;     }
;     EPI_ZERO_INIT
;     __device__ __forceinline__ void operator()(AccRef acc, const Unit& u, int sw) const {
;     ...
;             for (int m = 0; m < 4; ++m) { bf16_t* rowp = UG + (size_t)(row0 + ai * HALF + m * 16) * E + c0;
;                 float y[8];
; #pragma unroll
;                 for (int n = 0; n < 2; ++n)
; #pragma unroll
;                     for (int jp = 0; jp < 2; ++jp) {
;                         const f32x2 uu = (f32x2){acc[ai][0][m][n][2 * jp], acc[ai][0][m][n][2 * jp + 1]}, gg = (f32x2){acc[ai][1][m][n][2 * jp], acc[ai][1][m][n][2 * jp + 1]};
;                         const f32x2 za = (uu * uu * 0.044715f + 1.0f) * uu * (-1.44269504f * 1.59576912f), zg = gg * (-1.44269504f);
;                         f32x2 ea, eg; ea.x = __builtin_amdgcn_exp2f(za.x); ea.y = __builtin_amdgcn_exp2f(za.y); eg.x = __builtin_amdgcn_exp2f(zg.x); eg.y = __builtin_amdgcn_exp2f(zg.y);
;                         const f32x2 den = (ea + 1.0f) * (eg + 1.0f);
;                         f32x2 rc; rc.x = __builtin_amdgcn_rcpf(den.x); rc.y = __builtin_amdgcn_rcpf(den.y);
;                         const f32x2 yy = uu * gg * rc;
;                         y[4 * n + 2 * jp] = yy.x; y[4 * n + 2 * jp + 1] = yy.y; }
;                 u32x4 w; w.x = cvt_pk_bf16(y[0], y[1]); w.y = cvt_pk_bf16(y[2], y[3]); w.z = cvt_pk_bf16(y[4], y[5]); w.w = cvt_pk_bf16(y[6], y[7]);
;                 *(u32x4*)rowp = w; }
	v_exp_f32_e32 v30, v30
	v_exp_f32_e32 v31, v31
	v_pk_mul_f32 v[28:29], v[32:33], v[28:29]
	v_pk_mul_f32 v[32:33], v[22:23], v[22:23]
	v_pk_add_f32 v[34:35], v[34:35], 1.0 op_sel_hi:[1,0]
	v_pk_fma_f32 v[32:33], v[32:33], s[22:23], 1.0 op_sel_hi:[1,0,0]
	v_pk_add_f32 v[30:31], v[30:31], 1.0 op_sel_hi:[1,0]
	v_pk_mul_f32 v[32:33], v[22:23], v[32:33]
	v_pk_mul_f32 v[30:31], v[30:31], v[34:35]
	v_pk_mul_f32 v[32:33], v[32:33], s[84:85] op_sel_hi:[1,0]
	v_pk_mul_f32 v[34:35], v[18:19], s[74:75] op_sel_hi:[1,0]
	v_exp_f32_e32 v32, v32
	v_exp_f32_e32 v33, v33
	v_exp_f32_e32 v34, v34
	v_exp_f32_e32 v35, v35
	v_rcp_f32_e32 v30, v30
	v_pk_add_f32 v[32:33], v[32:33], 1.0 op_sel_hi:[1,0]
	v_rcp_f32_e32 v31, v31
	v_pk_add_f32 v[34:35], v[34:35], 1.0 op_sel_hi:[1,0]
	v_pk_mul_f32 v[18:19], v[22:23], v[18:19]
	v_pk_mul_f32 v[32:33], v[32:33], v[34:35]
	v_pk_mul_f32 v[28:29], v[28:29], v[30:31]
	v_rcp_f32_e32 v32, v32
	v_rcp_f32_e32 v33, v33
	v_pk_mul_f32 v[30:31], v[24:25], v[24:25]
	v_pk_mul_f32 v[36:37], v[36:37], s[84:85] op_sel_hi:[1,0]
	v_exp_f32_e32 v39, v39
	v_pk_mul_f32 v[22:23], v[18:19], v[32:33]
	v_pk_fma_f32 v[18:19], v[30:31], s[22:23], 1.0 op_sel_hi:[1,0,0]
	v_pk_mul_f32 v[30:31], v[20:21], s[74:75] op_sel_hi:[1,0]
	v_pk_mul_f32 v[18:19], v[24:25], v[18:19]
	v_exp_f32_e32 v36, v36
	v_pk_mul_f32 v[18:19], v[18:19], s[84:85] op_sel_hi:[1,0]
	v_exp_f32_e32 v37, v37
	v_exp_f32_e32 v18, v18
	v_exp_f32_e32 v19, v19
	v_exp_f32_e32 v30, v30
	v_exp_f32_e32 v31, v31
	v_pk_add_f32 v[36:37], v[36:37], 1.0 op_sel_hi:[1,0]
	v_pk_add_f32 v[38:39], v[38:39], 1.0 op_sel_hi:[1,0]
	v_pk_add_f32 v[18:19], v[18:19], 1.0 op_sel_hi:[1,0]
	v_pk_add_f32 v[30:31], v[30:31], 1.0 op_sel_hi:[1,0]
	v_pk_mul_f32 v[36:37], v[36:37], v[38:39]
	v_pk_mul_f32 v[18:19], v[18:19], v[30:31]
	v_rcp_f32_e32 v36, v36
	v_rcp_f32_e32 v37, v37
	v_rcp_f32_e32 v18, v18
	v_rcp_f32_e32 v19, v19
	v_pk_mul_f32 v[20:21], v[24:25], v[20:21]
	v_pk_mul_f32 v[26:27], v[26:27], v[36:37]
	v_pk_mul_f32 v[24:25], v[20:21], v[18:19]
	v_cvt_pk_bf16_f32 v18, v26, v27
	v_cvt_pk_bf16_f32 v19, v28, v29
	v_cvt_pk_bf16_f32 v20, v22, v23
	v_add_co_u32_e32 v22, vcc, s13, v114
	v_cvt_pk_bf16_f32 v21, v24, v25
	s_nop 1
	v_addc_co_u32_e32 v23, vcc, 0, v115, vcc
	global_store_dwordx4 v[22:23], v[18:21], off
	v_pk_mul_f32 v[22:23], v[10:11], s[74:75] op_sel_hi:[1,0]
	v_pk_mul_f32 v[10:11], v[14:15], v[10:11]
	v_pk_mul_f32 v[20:21], v[14:15], v[14:15]
	v_pk_mul_f32 v[18:19], v[16:17], v[16:17]
	v_pk_fma_f32 v[20:21], v[20:21], s[22:23], 1.0 op_sel_hi:[1,0,0]
	v_exp_f32_e32 v22, v22
	v_pk_mul_f32 v[20:21], v[14:15], v[20:21]
	v_pk_fma_f32 v[14:15], v[18:19], s[22:23], 1.0 op_sel_hi:[1,0,0]
	v_pk_mul_f32 v[18:19], v[12:13], s[74:75] op_sel_hi:[1,0]
	v_pk_mul_f32 v[14:15], v[16:17], v[14:15]
	v_exp_f32_e32 v18, v18
	v_pk_mul_f32 v[14:15], v[14:15], s[84:85] op_sel_hi:[1,0]
	v_exp_f32_e32 v19, v19
	v_exp_f32_e32 v14, v14
	v_exp_f32_e32 v15, v15
	v_pk_mul_f32 v[12:13], v[16:17], v[12:13]
	v_pk_mul_f32 v[16:17], v[6:7], v[6:7]
	v_pk_add_f32 v[18:19], v[18:19], 1.0 op_sel_hi:[1,0]
	v_pk_fma_f32 v[16:17], v[16:17], s[22:23], 1.0 op_sel_hi:[1,0,0]
	v_pk_add_f32 v[14:15], v[14:15], 1.0 op_sel_hi:[1,0]
	v_pk_mul_f32 v[16:17], v[6:7], v[16:17]
	v_pk_mul_f32 v[14:15], v[14:15], v[18:19]
	v_pk_mul_f32 v[16:17], v[16:17], s[84:85] op_sel_hi:[1,0]
	v_pk_mul_f32 v[18:19], v[2:3], s[74:75] op_sel_hi:[1,0]
	v_exp_f32_e32 v16, v16
	v_exp_f32_e32 v17, v17
	v_exp_f32_e32 v18, v18
	v_exp_f32_e32 v19, v19
	v_rcp_f32_e32 v14, v14
	v_pk_add_f32 v[16:17], v[16:17], 1.0 op_sel_hi:[1,0]
	v_rcp_f32_e32 v15, v15
	v_pk_add_f32 v[18:19], v[18:19], 1.0 op_sel_hi:[1,0]
	v_pk_mul_f32 v[2:3], v[6:7], v[2:3]
	v_pk_mul_f32 v[16:17], v[16:17], v[18:19]
	v_pk_mul_f32 v[12:13], v[12:13], v[14:15]
	v_rcp_f32_e32 v16, v16
	v_rcp_f32_e32 v17, v17
	v_pk_mul_f32 v[14:15], v[8:9], v[8:9]
	v_pk_mul_f32 v[20:21], v[20:21], s[84:85] op_sel_hi:[1,0]
	v_exp_f32_e32 v23, v23
	v_pk_mul_f32 v[6:7], v[2:3], v[16:17]
	v_pk_fma_f32 v[2:3], v[14:15], s[22:23], 1.0 op_sel_hi:[1,0,0]
	v_pk_mul_f32 v[14:15], v[4:5], s[74:75] op_sel_hi:[1,0]
	v_pk_mul_f32 v[2:3], v[8:9], v[2:3]
	v_exp_f32_e32 v20, v20
	v_pk_mul_f32 v[2:3], v[2:3], s[84:85] op_sel_hi:[1,0]
	v_exp_f32_e32 v21, v21
	v_exp_f32_e32 v2, v2
	v_exp_f32_e32 v3, v3
	v_exp_f32_e32 v14, v14
	v_exp_f32_e32 v15, v15
	v_pk_add_f32 v[20:21], v[20:21], 1.0 op_sel_hi:[1,0]
	v_pk_add_f32 v[22:23], v[22:23], 1.0 op_sel_hi:[1,0]
	v_pk_add_f32 v[2:3], v[2:3], 1.0 op_sel_hi:[1,0]
	v_pk_add_f32 v[14:15], v[14:15], 1.0 op_sel_hi:[1,0]
	v_pk_mul_f32 v[20:21], v[20:21], v[22:23]
	v_pk_mul_f32 v[2:3], v[2:3], v[14:15]
	v_rcp_f32_e32 v20, v20
	v_rcp_f32_e32 v21, v21
	v_rcp_f32_e32 v2, v2
	v_rcp_f32_e32 v3, v3
	v_pk_mul_f32 v[4:5], v[8:9], v[4:5]
	v_pk_mul_f32 v[10:11], v[10:11], v[20:21]
	v_pk_mul_f32 v[8:9], v[4:5], v[2:3]
	v_cvt_pk_bf16_f32 v2, v10, v11
	v_cvt_pk_bf16_f32 v3, v12, v13
	v_cvt_pk_bf16_f32 v4, v6, v7
	v_add_co_u32_e32 v6, vcc, 0x80c00, v114
	v_cvt_pk_bf16_f32 v5, v8, v9
	s_nop 1
	v_addc_co_u32_e32 v7, vcc, 0, v115, vcc
	global_store_dwordx4 v[6:7], v[2:5], off
	s_and_b64 vcc, exec, s[4:5]
	s_mov_b32 s50, s12
	s_mov_b32 s22, s16
	s_mov_b64 s[26:27], s[20:21]
	s_mov_b64 s[24:25], s[18:19]
	s_cbranch_vccz .LBB0_753
	s_waitcnt vmcnt(0)
	s_cmpk_gt_u32 s36, 0xff
	s_cbranch_scc1 .LBB0_760
	s_barrier

; #define LAS __attribute__((address_space(3)))
; __device__ __forceinline__ int ltid(int sw) { unsigned z = 0u; asm volatile("" : "+s"(sw), "+s"(z)); int t = sw * 64 + (int)__builtin_amdgcn_mbcnt_hi(~0u, __builtin_amdgcn_mbcnt_lo(~0u, z)); asm volatile("" : "+v"(t)); return t; }
; __device__ __forceinline__ View lview(View v) { asm volatile("" : "+s"(v.vb), "+s"(v.vG), "+s"(v.row0), "+s"(v.MR)); return v; }
; __device__ __forceinline__ void spatial_phase(int j, const bf16_t* UG, bf16_t* Y, const bf16_t* Vt, LAS unsigned char* lds, int sw, View vw) {
;     vw = lview(vw);
;     const int tid = ltid(sw), bid = vw.vb, nblk = vw.vG;
;     const int wave = __builtin_amdgcn_readfirstlane(tid >> 6), lane = tid & 63, fr = lane & 15, fq = lane >> 4;
;     const f32x2* VSTAT = (const f32x2*)(ARG_WS + WS_VSTAT);
;     const float* aws = argp(I_AWS) + (size_t)j * 8 * 128 * 128; const float* abs_ = argp(I_ABS) + (size_t)j * 8 * 128;
;     constexpr int WPITCH = 272, WPB = 128 * WPITCH;
;     LAS float* MU = (LAS float*)(lds + 2 * WPB); LAS float* RS = MU + 128; LAS float* M2 = MU + 256;
;     const float* gamma = argp(I_AVN) + j * E;
;     const int vrow = 8 * (fr >> 2) + (fr & 3);
;     for (int chunk = (vw.row0 >> 7) + bid; chunk < ((vw.row0 + vw.MR) >> 7); chunk += nblk) {
;         const int tok0 = chunk * 128;
.LBB0_867:
	s_mov_b32 s0, s75
	s_mov_b32 s1, s81
	s_ashr_i32 s69, s12, 7
	v_mbcnt_lo_u32_b32 v0, -1, s1
	v_mbcnt_hi_u32_b32 v0, -1, v0
	s_add_i32 s12, s12, s13
	v_lshl_add_u32 v2, s0, 6, v0
	s_add_i32 s94, s69, s68
	s_ashr_i32 s80, s12, 7
	s_mov_b64 s[8:9], s[92:93]
	v_readfirstlane_b32 s70, v2
	s_mov_b64 s[10:11], s[92:93]
	s_mov_b64 s[6:7], s[92:93]
	s_mov_b64 s[0:1], s[92:93]
	s_cmp_ge_i32 s94, s80
	s_cbranch_scc1 .LBB0_1011
; __device__ __forceinline__ void build_wp(const float* wsrc_g, LAS unsigned char* WPb, LAS float* M2b, const LAS float* MU, const LAS float* RS, int tid) {
;     const int t = tid >> 2, part = tid & 3, s0 = 32 * part;
;     const float* wsrc = wsrc_g + t * 128 + s0;
;     float m2 = 0.f;
; #pragma unroll
;     for (int q = 0; q < 4; ++q) { const f32x4 w0 = *(const f32x4*)(wsrc + 8 * q), w1 = *(const f32x4*)(wsrc + 8 * q + 4);
;         const float wv[8] = {w0[0], w0[1], w0[2], w0[3], w1[0], w1[1], w1[2], w1[3]};
;         unsigned pk[4];
; #pragma unroll
;         for (int e = 0; e < 8; e += 2) { const int s = s0 + 8 * q + e;
;             const float x0 = (s <= t) ? wv[e] * RS[s] : 0.f, x1 = (s + 1 <= t) ? wv[e + 1] * RS[s + 1] : 0.f;
;             const unsigned p = cvt_pk_bf16(x0, x1); pk[e >> 1] = p;
;             m2 += bf_lo(p) * MU[s] + bf_hi(p) * MU[s + 1]; }
;         *(LAS u32x4*)(WPb + t * 272 + (s0 + 8 * q) * 2) = (u32x4){pk[0], pk[1], pk[2], pk[3]}; }
;     m2 += __shfl_xor(m2, 1); m2 += __shfl_xor(m2, 2);
;     if (part == 0) M2b[t] = m2;
; }
; __device__ __forceinline__ void spatial_phase(int j, const bf16_t* UG, bf16_t* Y, const bf16_t* Vt, LAS unsigned char* lds, int sw, View vw) {
;     vw = lview(vw);
;     const int tid = ltid(sw), bid = vw.vb, nblk = vw.vG;
;     const int wave = __builtin_amdgcn_readfirstlane(tid >> 6), lane = tid & 63, fr = lane & 15, fq = lane >> 4;
;     const f32x2* VSTAT = (const f32x2*)(ARG_WS + WS_VSTAT);
;     const float* aws = argp(I_AWS) + (size_t)j * 8 * 128 * 128; const float* abs_ = argp(I_ABS) + (size_t)j * 8 * 128;
;     constexpr int WPITCH = 272, WPB = 128 * WPITCH;
;     LAS float* MU = (LAS float*)(lds + 2 * WPB); LAS float* RS = MU + 128; LAS float* M2 = MU + 256;
;     const float* gamma = argp(I_AVN) + j * E;
;     const int vrow = 8 * (fr >> 2) + (fr & 3);
;     for (int chunk = (vw.row0 >> 7) + bid; chunk < ((vw.row0 + vw.MR) >> 7); chunk += nblk) {
;         const int tok0 = chunk * 128;
;         __syncthreads();
;         if (tid < 128) { float s = 0.f, q = 0.f;
; #pragma unroll
;             for (int p = 0; p < 16; ++p) { const f32x2 v = VSTAT[(size_t)p * M + tok0 + tid]; s += v[0]; q += v[1]; }
;             const float mu = s * (1.0f / E), var = q * (1.0f / E) - mu * mu;
;             MU[tid] = mu; RS[tid] = 1.0f / sqrtf(var + EPS); }
;         __syncthreads();
	s_load_dwordx2 s[8:9], s[8:9], 0xa8
	v_ashrrev_i32_e32 v3, 31, v2
	s_load_dwordx2 s[66:67], s[10:11], 0x40
	s_load_dwordx2 s[54:55], s[0:1], 0x38
	s_movk_i32 s0, 0x80
	s_load_dwordx2 s[58:59], s[6:7], 0x48
	v_readlane_b32 s6, v255, 26
	v_cmp_gt_i32_e64 s[0:1], s0, v2
	v_readlane_b32 s7, v255, 27
	s_mov_b32 s15, s81
	v_writelane_b32 v255, s0, 28
	s_waitcnt lgkmcnt(0)
	v_lshl_add_u64 v[4:5], v[2:3], 3, s[8:9]
	v_ashrrev_i32_e32 v3, 2, v2
	v_writelane_b32 v255, s1, 29
	s_mov_b64 s[0:1], 0x200000
	s_lshl_b64 s[10:11], s[14:15], 19
	v_lshl_add_u64 v[138:139], v[4:5], 0, s[0:1]
	v_lshlrev_b32_e32 v4, 7, v3
	s_add_u32 s10, s66, s10
	v_ashrrev_i32_e32 v5, 31, v4
	s_addc_u32 s11, s67, s11
	v_and_b32_e32 v17, 3, v2
	v_lshlrev_b32_e32 v0, 2, v2
	v_readlane_b32 s76, v255, 15
	v_readlane_b32 s77, v255, 16
	v_lshlrev_b64 v[4:5], 2, v[4:5]
	v_add_u32_e32 v171, s76, v0
	v_add_u32_e32 v172, s77, v0
	v_lshl_add_u64 v[6:7], s[10:11], 0, v[4:5]
	v_lshlrev_b32_e32 v0, 7, v17
	s_movk_i32 s0, 0x110
	v_lshl_add_u64 v[140:141], v[6:7], 0, v[0:1]
	v_mul_lo_u32 v6, v3, s0
	s_ashr_i32 s0, s70, 1
	s_lshr_b64 s[6:7], s[6:7], 1
	s_andn2_b32 s0, s0, 31
	s_lshl_b64 s[62:63], s[6:7], 12
	s_lshl_b64 s[64:65], s[6:7], 19
	s_lshl_b64 s[56:57], s[6:7], 13
	s_ashr_i32 s1, s0, 31
	s_add_u32 s62, s58, s62
	v_lshlrev_b32_e32 v13, 5, v17
	s_addc_u32 s63, s59, s63
	s_ashr_i32 s59, s68, 31
	s_ashr_i32 s70, s69, 31
	v_or_b32_e32 v7, 2, v13
	s_add_u32 s58, s68, s69
	v_cmp_le_i32_e64 s[10:11], v7, v3
	v_lshlrev_b32_e32 v9, 2, v7
	v_cmp_lt_i32_e64 s[12:13], v7, v3
	v_or_b32_e32 v7, 4, v13
	s_addc_u32 s59, s59, s70
	v_add_u32_e32 v176, s77, v9
	v_add_u32_e32 v178, s76, v9
	v_cmp_le_i32_e64 s[14:15], v7, v3
	v_lshlrev_b32_e32 v9, 2, v7
	s_mov_b32 s88, s16
	v_cmp_lt_i32_e64 s[16:17], v7, v3
	v_or_b32_e32 v7, 6, v13
	s_lshl_b64 s[58:59], s[58:59], 19
	s_lshl_b64 s[68:69], s[0:1], 8
	v_add_u32_e32 v179, s77, v9
	v_add_u32_e32 v181, s76, v9
	v_cmp_le_i32_e64 s[18:19], v7, v3
	v_lshlrev_b32_e32 v9, 2, v7
	v_cmp_lt_i32_e64 s[20:21], v7, v3
	v_lshlrev_b32_e32 v7, 6, v17
	s_add_u32 s58, s58, s68
	v_add3_u32 v185, 0, v6, v7
	v_or_b32_e32 v6, 8, v13
	s_addc_u32 s59, s59, s69
	v_cmp_le_i32_e64 s[22:23], v6, v3
	v_lshlrev_b32_e32 v7, 2, v6
	v_cmp_lt_i32_e64 s[24:25], v6, v3
	v_or_b32_e32 v6, 10, v13
	s_add_u32 s68, s60, s58
	v_add_u32_e32 v186, s77, v7
	v_add_u32_e32 v188, s76, v7
	v_cmp_le_i32_e64 s[26:27], v6, v3
	v_lshlrev_b32_e32 v7, 2, v6
	v_cmp_lt_i32_e64 s[28:29], v6, v3
	v_or_b32_e32 v6, 12, v13
	s_addc_u32 s69, s61, s59
	s_ashr_i32 s89, s88, 31
	v_add_u32_e32 v189, s77, v7
	v_add_u32_e32 v191, s76, v7
	v_cmp_le_i32_e64 s[30:31], v6, v3
	v_lshlrev_b32_e32 v7, 2, v6
	v_cmp_lt_i32_e64 s[34:35], v6, v3
	v_or_b32_e32 v6, 14, v13
	s_lshl_b64 s[58:59], s[88:89], 19
	v_add_u32_e32 v192, s77, v7
	v_add_u32_e32 v194, s76, v7
	v_cmp_le_i32_e64 s[36:37], v6, v3
	v_lshlrev_b32_e32 v7, 2, v6
	v_cmp_lt_i32_e64 s[38:39], v6, v3
	v_or_b32_e32 v6, 16, v13
	v_writelane_b32 v255, s58, 30
	v_add_u32_e32 v195, s77, v7
	v_add_u32_e32 v197, s76, v7
	v_cmp_le_i32_e64 s[40:41], v6, v3
	v_lshlrev_b32_e32 v7, 2, v6
	v_cmp_lt_i32_e64 s[42:43], v6, v3
	v_or_b32_e32 v6, 18, v13
	v_writelane_b32 v255, s59, 31
	s_lshl_b64 s[58:59], s[0:1], 2
	v_add_u32_e32 v198, s77, v7
	v_add_u32_e32 v200, s76, v7
	v_cmp_le_i32_e64 s[44:45], v6, v3
	v_lshlrev_b32_e32 v7, 2, v6
	v_cmp_lt_i32_e64 s[46:47], v6, v3
	v_or_b32_e32 v6, 20, v13
	s_add_u32 s58, s54, s58
	v_add_u32_e32 v201, s77, v7
	v_add_u32_e32 v203, s76, v7
	v_cmp_le_i32_e64 s[48:49], v6, v3
	v_lshlrev_b32_e32 v7, 2, v6
	v_cmp_lt_i32_e64 s[50:51], v6, v3
	v_or_b32_e32 v6, 22, v13
	s_addc_u32 s59, s55, s59
	v_add_u32_e32 v204, s77, v7
	v_add_u32_e32 v206, s76, v7
	v_cmp_le_i32_e64 s[52:53], v6, v3
	v_lshlrev_b32_e32 v7, 2, v6
	v_cmp_lt_i32_e64 s[54:55], v6, v3
	v_or_b32_e32 v6, 24, v13
	s_add_u32 s70, s58, s56
	v_add_u32_e32 v207, s77, v7
	v_add_u32_e32 v209, s76, v7
	s_addc_u32 s71, s59, s57
	v_cmp_le_i32_e64 s[56:57], v6, v3
	v_lshlrev_b32_e32 v7, 2, v6
	v_cmp_lt_i32_e64 s[58:59], v6, v3
	v_lshrrev_b32_e32 v6, 1, v2
	v_lshlrev_b32_e32 v12, 1, v2
	v_and_b32_e32 v14, 24, v6
	v_and_b32_e32 v16, 15, v2
	v_and_or_b32 v8, v12, 24, v17
	v_or_b32_e32 v10, 26, v13
	v_lshlrev_b32_e32 v18, 1, v14
	v_add_u32_e32 v182, s77, v9
	v_add_u32_e32 v184, s76, v9
	v_add_u32_e32 v210, s77, v7
	v_add_u32_e32 v212, s76, v7
	v_lshl_or_b32 v6, v8, 8, v18
	v_mov_b32_e32 v7, v1
	v_lshlrev_b32_e32 v11, 2, v10
	v_lshlrev_b32_e32 v8, 2, v16
	v_mov_b32_e32 v9, v1
	v_lshl_add_u64 v[6:7], s[60:61], 0, v[6:7]
	v_cmp_le_i32_e64 s[60:61], v10, v3
	v_add_u32_e32 v213, s77, v11
	v_lshl_add_u64 v[142:143], s[62:63], 0, v[8:9]
	v_cmp_lt_i32_e64 s[62:63], v10, v3
	v_add_u32_e32 v215, s76, v11
	v_or_b32_e32 v10, s64, v0
	v_mov_b32_e32 v11, s65
	v_or_b32_e32 v9, 28, v13
	v_lshl_add_u64 v[4:5], v[10:11], 0, v[4:5]
	v_lshlrev_b32_e32 v10, 8, v2
	v_cmp_le_i32_e64 s[64:65], v9, v3
	v_lshlrev_b32_e32 v15, 2, v9
	v_lshl_add_u64 v[4:5], s[66:67], 0, v[4:5]
	v_cmp_lt_i32_e64 s[66:67], v9, v3
	v_or_b32_e32 v9, 30, v13
	v_and_b32_e32 v10, 0xc00, v10
	v_add_u32_e32 v173, s77, v0
	v_add_u32_e32 v175, s76, v0
	v_or3_b32 v0, v10, v0, v14
	v_lshlrev_b32_e32 v14, 2, v9
	v_add_u32_e32 v216, s77, v15
	v_add_u32_e32 v218, s76, v15
	v_add_u32_e32 v219, s77, v14
	v_add_u32_e32 v221, s76, v14
	s_mov_b64 s[76:77], 0xe000000
	v_lshlrev_b32_e32 v0, 1, v0
	v_lshl_add_u64 v[146:147], v[6:7], 0, s[76:77]
	s_mov_b64 s[76:77], 0x10040
	v_lshl_add_u64 v[10:11], s[68:69], 0, v[0:1]
	v_and_b32_e32 v0, 0x60, v12
	v_lshl_add_u64 v[148:149], v[4:5], 0, s[76:77]
	s_mov_b64 s[76:77], 0xe010400
	v_cmp_le_i32_e64 s[6:7], v13, v3
	v_cmp_lt_i32_e64 s[8:9], v13, v3
	v_lshl_add_u64 v[12:13], s[70:71], 0, v[0:1]
	v_lshl_or_b32 v0, v16, 12, v18
	v_lshl_add_u64 v[150:151], v[10:11], 0, s[76:77]
	s_mov_b32 s76, s88
	v_lshl_add_u64 v[14:15], s[0:1], 1, v[0:1]
	v_and_b32_e32 v0, -4, v2
	v_readlane_b32 s82, v255, 17
	v_writelane_b32 v255, s76, 32
	v_add_u32_e32 v174, 4, v173
	v_add_u32_e32 v177, 12, v173
	v_add_u32_e32 v180, 20, v173
	v_add_u32_e32 v183, 28, v173
	v_add_u32_e32 v187, 36, v173
	v_add_u32_e32 v190, 44, v173
	v_add_u32_e32 v193, 52, v173
	v_add_u32_e32 v196, 60, v173
	v_add_u32_e32 v199, 0x44, v173
	v_add_u32_e32 v202, 0x4c, v173
	v_add_u32_e32 v205, 0x54, v173
	v_add_u32_e32 v208, 0x5c, v173
	v_add_u32_e32 v211, 0x64, v173
	v_add_u32_e32 v214, 0x6c, v173
	v_add_u32_e32 v217, 0x74, v173
	v_cmp_le_i32_e64 s[68:69], v9, v3
	v_cmp_lt_i32_e64 s[70:71], v9, v3
	v_add_u32_e32 v220, 0x7c, v173
	v_lshl_add_u64 v[144:145], s[72:73], 0, v[14:15]
	v_cmp_eq_u32_e64 s[72:73], 0, v17
	v_add_u32_e32 v0, s82, v0
	v_add_u32_e32 v222, 0, v18
	v_mul_u32_u24_e32 v223, 0x110, v16
	v_add_u32_e32 v224, s82, v8
	v_lshl_add_u64 v[152:153], v[12:13], 0, 16
	v_and_b32_e32 v154, 63, v2
	v_lshlrev_b32_e32 v154, 4, v154
	v_lshl_or_b32 v154, s0, 8, v154
	v_mov_b32_e32 v155, 0
	v_lshl_add_u64 v[154:155], s[4:5], 0, v[154:155]
	s_lshl_b32 s4, s94, 7
	v_writelane_b32 v255, s77, 33
	s_lshl_b32 s91, s88, 7
	s_branch .LBB0_870

; #define LAS __attribute__((address_space(3)))
; __device__ __forceinline__ unsigned cvt_pk_bf16(float lo, float hi) { unsigned r; asm volatile("v_cvt_pk_bf16_f32 %0, %1, %2" : "=v"(r) : "v"(lo), "v"(hi)); return r; }
; __device__ __forceinline__ float bf_lo(unsigned w) { return __uint_as_float(w << 16); }
; __device__ __forceinline__ float bf_hi(unsigned w) { return __uint_as_float(w & 0xffff0000u); }
; __device__ __forceinline__ void build_wp(const float* wsrc_g, LAS unsigned char* WPb, LAS float* M2b, const LAS float* MU, const LAS float* RS, int tid) {
;     const int t = tid >> 2, part = tid & 3, s0 = 32 * part;
;     const float* wsrc = wsrc_g + t * 128 + s0;
;     float m2 = 0.f;
; #pragma unroll
;     for (int q = 0; q < 4; ++q) { const f32x4 w0 = *(const f32x4*)(wsrc + 8 * q), w1 = *(const f32x4*)(wsrc + 8 * q + 4);
;         const float wv[8] = {w0[0], w0[1], w0[2], w0[3], w1[0], w1[1], w1[2], w1[3]};
;         unsigned pk[4];
; #pragma unroll
;         for (int e = 0; e < 8; e += 2) { const int s = s0 + 8 * q + e;
;             const float x0 = (s <= t) ? wv[e] * RS[s] : 0.f, x1 = (s + 1 <= t) ? wv[e + 1] * RS[s + 1] : 0.f;
;             const unsigned p = cvt_pk_bf16(x0, x1); pk[e >> 1] = p;
;             m2 += bf_lo(p) * MU[s] + bf_hi(p) * MU[s + 1]; }
;         *(LAS u32x4*)(WPb + t * 272 + (s0 + 8 * q) * 2) = (u32x4){pk[0], pk[1], pk[2], pk[3]}; }
.LBB0_874:
	s_or_b64 exec, exec, s[76:77]
	s_and_saveexec_b64 s[76:77], s[8:9]
	s_cbranch_execz .LBB0_876
	ds_read_b32 v2, v173 offset:4
	s_waitcnt vmcnt(0) lgkmcnt(0)
	v_mul_f32_e32 v2, v9, v2
.LBB0_876:
	s_or_b64 exec, exec, s[76:77]
	v_cvt_pk_bf16_f32 v2, v3, v2
	ds_read_b64 v[24:25], v175
	v_mov_b32_e32 v3, 0
	s_waitcnt vmcnt(0)
	v_mov_b32_e32 v8, 0
	s_and_saveexec_b64 s[76:77], s[10:11]
	s_cbranch_execz .LBB0_878
	ds_read_b32 v8, v173 offset:8
	s_waitcnt lgkmcnt(0)
	v_mul_f32_e32 v8, v10, v8
.LBB0_878:
	s_or_b64 exec, exec, s[76:77]
	s_and_saveexec_b64 s[76:77], s[12:13]
	s_cbranch_execz .LBB0_880
	ds_read_b32 v3, v173 offset:12
	s_waitcnt lgkmcnt(0)
	v_mul_f32_e32 v3, v11, v3
.LBB0_880:
	s_or_b64 exec, exec, s[76:77]
	v_cvt_pk_bf16_f32 v3, v8, v3
	ds_read_b64 v[26:27], v175 offset:8
	v_mov_b32_e32 v8, 0
	v_mov_b32_e32 v9, 0
	s_and_saveexec_b64 s[76:77], s[14:15]
	s_cbranch_execz .LBB0_882
	ds_read_b32 v9, v173 offset:16
	s_waitcnt lgkmcnt(0)
	v_mul_f32_e32 v9, v4, v9
.LBB0_882:
	s_or_b64 exec, exec, s[76:77]
	s_and_saveexec_b64 s[76:77], s[16:17]
	s_cbranch_execz .LBB0_884
	ds_read_b32 v4, v173 offset:20
	s_waitcnt lgkmcnt(0)
	v_mul_f32_e32 v8, v5, v4
.LBB0_884:
	s_or_b64 exec, exec, s[76:77]
	v_cvt_pk_bf16_f32 v4, v9, v8
	ds_read_b64 v[28:29], v175 offset:16
	v_mov_b32_e32 v5, 0
	v_mov_b32_e32 v8, 0
	s_and_saveexec_b64 s[76:77], s[18:19]
	s_cbranch_execz .LBB0_886
	ds_read_b32 v8, v173 offset:24
	s_waitcnt lgkmcnt(0)
	v_mul_f32_e32 v8, v6, v8
.LBB0_886:
	s_or_b64 exec, exec, s[76:77]
	s_and_saveexec_b64 s[76:77], s[20:21]
	s_cbranch_execz .LBB0_888
	ds_read_b32 v5, v173 offset:28
	s_waitcnt lgkmcnt(0)
	v_mul_f32_e32 v5, v7, v5
.LBB0_888:
	s_or_b64 exec, exec, s[76:77]
	v_cvt_pk_bf16_f32 v5, v8, v5
	global_load_dwordx4 v[8:11], v[140:141], off offset:48
	global_load_dwordx4 v[12:15], v[140:141], off offset:32
	ds_read_b64 v[30:31], v175 offset:24
	v_mov_b32_e32 v6, 0
	v_mov_b32_e32 v7, 0
	ds_write_b128 v185, v[2:5]
	s_and_saveexec_b64 s[76:77], s[22:23]
	s_cbranch_execz .LBB0_890
	ds_read_b32 v7, v173 offset:32
	s_waitcnt vmcnt(0) lgkmcnt(0)
	v_mul_f32_e32 v7, v12, v7
.LBB0_890:
	s_or_b64 exec, exec, s[76:77]
	s_and_saveexec_b64 s[76:77], s[24:25]
	s_cbranch_execz .LBB0_892
	ds_read_b32 v6, v173 offset:36
	s_waitcnt vmcnt(0) lgkmcnt(0)
	v_mul_f32_e32 v6, v13, v6
.LBB0_892:
	s_or_b64 exec, exec, s[76:77]
	v_cvt_pk_bf16_f32 v6, v7, v6
	ds_read_b64 v[32:33], v175 offset:32
	v_mov_b32_e32 v7, 0
	s_waitcnt vmcnt(0)
	v_mov_b32_e32 v12, 0
	s_and_saveexec_b64 s[76:77], s[26:27]
	s_cbranch_execz .LBB0_894
	ds_read_b32 v12, v173 offset:40
	s_waitcnt lgkmcnt(0)
	v_mul_f32_e32 v12, v14, v12
.LBB0_894:
	s_or_b64 exec, exec, s[76:77]
	s_and_saveexec_b64 s[76:77], s[28:29]
	s_cbranch_execz .LBB0_896
	ds_read_b32 v7, v173 offset:44
	s_waitcnt lgkmcnt(0)
	v_mul_f32_e32 v7, v15, v7
.LBB0_896:
	s_or_b64 exec, exec, s[76:77]
	v_cvt_pk_bf16_f32 v7, v12, v7
	ds_read_b64 v[34:35], v175 offset:40
	v_mov_b32_e32 v12, 0
	v_mov_b32_e32 v13, 0
	s_and_saveexec_b64 s[76:77], s[30:31]
	s_cbranch_execz .LBB0_898
	ds_read_b32 v13, v173 offset:48
	s_waitcnt lgkmcnt(0)
	v_mul_f32_e32 v13, v8, v13
.LBB0_898:
	s_or_b64 exec, exec, s[76:77]
	s_and_saveexec_b64 s[76:77], s[34:35]
	s_cbranch_execz .LBB0_900
	ds_read_b32 v8, v173 offset:52
	s_waitcnt lgkmcnt(0)
	v_mul_f32_e32 v12, v9, v8
.LBB0_900:
	s_or_b64 exec, exec, s[76:77]
	v_cvt_pk_bf16_f32 v8, v13, v12
	ds_read_b64 v[36:37], v175 offset:48
	v_mov_b32_e32 v9, 0
	v_mov_b32_e32 v12, 0
	s_and_saveexec_b64 s[76:77], s[36:37]
	s_cbranch_execz .LBB0_902
	ds_read_b32 v12, v173 offset:56
	s_waitcnt lgkmcnt(0)
	v_mul_f32_e32 v12, v10, v12
.LBB0_902:
	s_or_b64 exec, exec, s[76:77]
	s_and_saveexec_b64 s[76:77], s[38:39]
	s_cbranch_execz .LBB0_904
	ds_read_b32 v9, v173 offset:60
	s_waitcnt lgkmcnt(0)
	v_mul_f32_e32 v9, v11, v9
.LBB0_904:
	s_or_b64 exec, exec, s[76:77]
	v_cvt_pk_bf16_f32 v9, v12, v9
	global_load_dwordx4 v[12:15], v[140:141], off offset:80
	global_load_dwordx4 v[16:19], v[140:141], off offset:64
	ds_read_b64 v[38:39], v175 offset:56
	v_mov_b32_e32 v10, 0
	v_mov_b32_e32 v11, 0
	ds_write_b128 v185, v[6:9] offset:16
	s_and_saveexec_b64 s[76:77], s[40:41]
	s_cbranch_execz .LBB0_906
	ds_read_b32 v11, v173 offset:64
	s_waitcnt vmcnt(0) lgkmcnt(0)
	v_mul_f32_e32 v11, v16, v11
.LBB0_906:
	s_or_b64 exec, exec, s[76:77]
	s_and_saveexec_b64 s[76:77], s[42:43]
	s_cbranch_execz .LBB0_908
	ds_read_b32 v10, v173 offset:68
	s_waitcnt vmcnt(0) lgkmcnt(0)
	v_mul_f32_e32 v10, v17, v10
.LBB0_908:
	s_or_b64 exec, exec, s[76:77]
	v_cvt_pk_bf16_f32 v10, v11, v10
	ds_read_b64 v[40:41], v175 offset:64
	v_mov_b32_e32 v11, 0
	s_waitcnt vmcnt(0)
	v_mov_b32_e32 v16, 0
	s_and_saveexec_b64 s[76:77], s[44:45]
	s_cbranch_execz .LBB0_910
	ds_read_b32 v16, v173 offset:72
	s_waitcnt lgkmcnt(0)
	v_mul_f32_e32 v16, v18, v16
.LBB0_910:
	s_or_b64 exec, exec, s[76:77]
	s_and_saveexec_b64 s[76:77], s[46:47]
	s_cbranch_execz .LBB0_912
	ds_read_b32 v11, v173 offset:76
	s_waitcnt lgkmcnt(0)
	v_mul_f32_e32 v11, v19, v11
.LBB0_912:
	s_or_b64 exec, exec, s[76:77]
	v_cvt_pk_bf16_f32 v11, v16, v11
	ds_read_b64 v[42:43], v175 offset:72
	v_mov_b32_e32 v16, 0
	v_mov_b32_e32 v17, 0
	s_and_saveexec_b64 s[76:77], s[48:49]
	s_cbranch_execz .LBB0_914
	ds_read_b32 v17, v173 offset:80
	s_waitcnt lgkmcnt(0)
	v_mul_f32_e32 v17, v12, v17
.LBB0_914:
	s_or_b64 exec, exec, s[76:77]
	s_and_saveexec_b64 s[76:77], s[50:51]
	s_cbranch_execz .LBB0_916
	ds_read_b32 v12, v173 offset:84
	s_waitcnt lgkmcnt(0)
	v_mul_f32_e32 v16, v13, v12
; #define LAS __attribute__((address_space(3)))
; __device__ __forceinline__ unsigned cvt_pk_bf16(float lo, float hi) { unsigned r; asm volatile("v_cvt_pk_bf16_f32 %0, %1, %2" : "=v"(r) : "v"(lo), "v"(hi)); return r; }
; __device__ __forceinline__ float bf_lo(unsigned w) { return __uint_as_float(w << 16); }
; __device__ __forceinline__ float bf_hi(unsigned w) { return __uint_as_float(w & 0xffff0000u); }
; __device__ __forceinline__ void build_wp(const float* wsrc_g, LAS unsigned char* WPb, LAS float* M2b, const LAS float* MU, const LAS float* RS, int tid) {
;     ...
;     for (int q = 0; q < 4; ++q) { const f32x4 w0 = *(const f32x4*)(wsrc + 8 * q), w1 = *(const f32x4*)(wsrc + 8 * q + 4);
;         const float wv[8] = {w0[0], w0[1], w0[2], w0[3], w1[0], w1[1], w1[2], w1[3]};
;         unsigned pk[4];
; #pragma unroll
;         for (int e = 0; e < 8; e += 2) { const int s = s0 + 8 * q + e;
;             const float x0 = (s <= t) ? wv[e] * RS[s] : 0.f, x1 = (s + 1 <= t) ? wv[e + 1] * RS[s + 1] : 0.f;
;             const unsigned p = cvt_pk_bf16(x0, x1); pk[e >> 1] = p;
;             m2 += bf_lo(p) * MU[s] + bf_hi(p) * MU[s + 1]; }
;         *(LAS u32x4*)(WPb + t * 272 + (s0 + 8 * q) * 2) = (u32x4){pk[0], pk[1], pk[2], pk[3]}; }
;     m2 += __shfl_xor(m2, 1); m2 += __shfl_xor(m2, 2);
;     if (part == 0) M2b[t] = m2;
.LBB0_916:
	s_or_b64 exec, exec, s[76:77]
	v_cvt_pk_bf16_f32 v12, v17, v16
	ds_read_b64 v[44:45], v175 offset:80
	v_mov_b32_e32 v13, 0
	v_mov_b32_e32 v16, 0
	s_and_saveexec_b64 s[76:77], s[52:53]
	s_cbranch_execz .LBB0_918
	ds_read_b32 v16, v173 offset:88
	s_waitcnt lgkmcnt(0)
	v_mul_f32_e32 v16, v14, v16
.LBB0_918:
	s_or_b64 exec, exec, s[76:77]
	s_and_saveexec_b64 s[76:77], s[54:55]
	s_cbranch_execz .LBB0_920
	ds_read_b32 v13, v173 offset:92
	s_waitcnt lgkmcnt(0)
	v_mul_f32_e32 v13, v15, v13
.LBB0_920:
	s_or_b64 exec, exec, s[76:77]
	v_cvt_pk_bf16_f32 v13, v16, v13
	global_load_dwordx4 v[16:19], v[140:141], off offset:112
	global_load_dwordx4 v[20:23], v[140:141], off offset:96
	ds_read_b64 v[46:47], v175 offset:88
	v_mov_b32_e32 v14, 0
	v_mov_b32_e32 v15, 0
	ds_write_b128 v185, v[10:13] offset:32
	s_and_saveexec_b64 s[76:77], s[56:57]
	s_cbranch_execz .LBB0_922
	ds_read_b32 v15, v173 offset:96
	s_waitcnt vmcnt(0) lgkmcnt(0)
	v_mul_f32_e32 v15, v20, v15
.LBB0_922:
	s_or_b64 exec, exec, s[76:77]
	s_and_saveexec_b64 s[76:77], s[58:59]
	s_cbranch_execz .LBB0_924
	ds_read_b32 v14, v173 offset:100
	s_waitcnt vmcnt(0) lgkmcnt(0)
	v_mul_f32_e32 v14, v21, v14
.LBB0_924:
	s_or_b64 exec, exec, s[76:77]
	v_cvt_pk_bf16_f32 v14, v15, v14
	s_waitcnt vmcnt(0)
	ds_read_b64 v[20:21], v175 offset:96
	v_mov_b32_e32 v15, 0
	v_mov_b32_e32 v48, 0
	s_and_saveexec_b64 s[76:77], s[60:61]
	s_cbranch_execz .LBB0_926
	ds_read_b32 v48, v173 offset:104
	s_waitcnt lgkmcnt(0)
	v_mul_f32_e32 v48, v22, v48
.LBB0_926:
	s_or_b64 exec, exec, s[76:77]
	s_and_saveexec_b64 s[76:77], s[62:63]
	s_cbranch_execz .LBB0_928
	ds_read_b32 v15, v173 offset:108
	s_waitcnt lgkmcnt(0)
	v_mul_f32_e32 v15, v23, v15
.LBB0_928:
	s_or_b64 exec, exec, s[76:77]
	v_cvt_pk_bf16_f32 v15, v48, v15
	ds_read_b64 v[22:23], v175 offset:104
	v_mov_b32_e32 v48, 0
	v_mov_b32_e32 v49, 0
	s_and_saveexec_b64 s[76:77], s[64:65]
	s_cbranch_execz .LBB0_930
	ds_read_b32 v49, v173 offset:112
	s_waitcnt lgkmcnt(0)
	v_mul_f32_e32 v49, v16, v49
.LBB0_930:
	s_or_b64 exec, exec, s[76:77]
	s_and_saveexec_b64 s[76:77], s[66:67]
	s_cbranch_execz .LBB0_932
	ds_read_b32 v16, v173 offset:116
	s_waitcnt lgkmcnt(0)
	v_mul_f32_e32 v48, v17, v16
.LBB0_932:
	s_or_b64 exec, exec, s[76:77]
	v_cvt_pk_bf16_f32 v16, v49, v48
	ds_read_b64 v[48:49], v175 offset:112
	v_mov_b32_e32 v17, 0
	v_mov_b32_e32 v50, 0
	s_and_saveexec_b64 s[76:77], s[68:69]
	s_cbranch_execz .LBB0_934
	ds_read_b32 v50, v173 offset:120
	s_waitcnt lgkmcnt(0)
	v_mul_f32_e32 v50, v18, v50
.LBB0_934:
	s_or_b64 exec, exec, s[76:77]
	s_and_saveexec_b64 s[76:77], s[70:71]
	s_cbranch_execz .LBB0_936
	ds_read_b32 v17, v173 offset:124
	s_waitcnt lgkmcnt(0)
	v_mul_f32_e32 v17, v19, v17
.LBB0_936:
	s_or_b64 exec, exec, s[76:77]
	v_lshlrev_b32_e32 v18, 16, v2
	v_and_b32_e32 v2, 0xffff0000, v2
	s_waitcnt lgkmcnt(14)
	v_mul_f32_e32 v2, v25, v2
	v_fmac_f32_e32 v2, v24, v18
	v_lshlrev_b32_e32 v18, 16, v3
	v_and_b32_e32 v3, 0xffff0000, v3
	v_mul_f32_e32 v3, v27, v3
	v_add_f32_e32 v2, 0, v2
	v_fmac_f32_e32 v3, v26, v18
	v_add_f32_e32 v2, v2, v3
	v_lshlrev_b32_e32 v3, 16, v4
	v_and_b32_e32 v4, 0xffff0000, v4
	v_mul_f32_e32 v4, v29, v4
	v_fmac_f32_e32 v4, v28, v3
	v_add_f32_e32 v2, v2, v4
	v_and_b32_e32 v4, 0xffff0000, v5
	v_lshlrev_b32_e32 v3, 16, v5
	v_mul_f32_e32 v4, v31, v4
	v_fmac_f32_e32 v4, v30, v3
	v_add_f32_e32 v2, v2, v4
	v_and_b32_e32 v4, 0xffff0000, v6
	v_lshlrev_b32_e32 v3, 16, v6
	s_waitcnt lgkmcnt(12)
	v_mul_f32_e32 v4, v33, v4
	v_fmac_f32_e32 v4, v32, v3
	v_add_f32_e32 v2, v2, v4
	v_and_b32_e32 v4, 0xffff0000, v7
	v_lshlrev_b32_e32 v3, 16, v7
	s_waitcnt lgkmcnt(11)
	v_mul_f32_e32 v4, v35, v4
	v_fmac_f32_e32 v4, v34, v3
	v_add_f32_e32 v2, v2, v4
	v_and_b32_e32 v4, 0xffff0000, v8
	v_lshlrev_b32_e32 v3, 16, v8
	s_waitcnt lgkmcnt(10)
	v_mul_f32_e32 v4, v37, v4
	v_fmac_f32_e32 v4, v36, v3
	v_add_f32_e32 v2, v2, v4
	v_and_b32_e32 v4, 0xffff0000, v9
	v_lshlrev_b32_e32 v3, 16, v9
	s_waitcnt lgkmcnt(9)
	v_mul_f32_e32 v4, v39, v4
	v_fmac_f32_e32 v4, v38, v3
	v_add_f32_e32 v2, v2, v4
	v_and_b32_e32 v4, 0xffff0000, v10
	v_lshlrev_b32_e32 v3, 16, v10
	s_waitcnt lgkmcnt(7)
	v_mul_f32_e32 v4, v41, v4
	v_fmac_f32_e32 v4, v40, v3
	v_add_f32_e32 v2, v2, v4
	v_and_b32_e32 v4, 0xffff0000, v11
	v_lshlrev_b32_e32 v3, 16, v11
	s_waitcnt lgkmcnt(6)
	v_mul_f32_e32 v4, v43, v4
	v_fmac_f32_e32 v4, v42, v3
	v_add_f32_e32 v2, v2, v4
	v_and_b32_e32 v4, 0xffff0000, v12
	v_lshlrev_b32_e32 v3, 16, v12
	s_waitcnt lgkmcnt(5)
	v_mul_f32_e32 v4, v45, v4
	v_fmac_f32_e32 v4, v44, v3
	v_add_f32_e32 v2, v2, v4
	v_and_b32_e32 v4, 0xffff0000, v13
	v_lshlrev_b32_e32 v3, 16, v13
	s_waitcnt lgkmcnt(4)
	v_mul_f32_e32 v4, v47, v4
	v_fmac_f32_e32 v4, v46, v3
	v_add_f32_e32 v2, v2, v4
	v_and_b32_e32 v4, 0xffff0000, v14
	v_lshlrev_b32_e32 v3, 16, v14
	s_waitcnt lgkmcnt(2)
	v_mul_f32_e32 v4, v21, v4
	v_fmac_f32_e32 v4, v20, v3
	v_add_f32_e32 v2, v2, v4
	v_and_b32_e32 v4, 0xffff0000, v15
	v_lshlrev_b32_e32 v3, 16, v15
	s_waitcnt lgkmcnt(1)
	v_mul_f32_e32 v4, v23, v4
	v_fmac_f32_e32 v4, v22, v3
	v_add_f32_e32 v4, v2, v4
	v_and_b32_e32 v2, 0xffff0000, v16
	s_waitcnt lgkmcnt(0)
	v_mul_f32_e32 v6, v49, v2
	v_cvt_pk_bf16_f32 v17, v50, v17
	ds_read_b64 v[2:3], v175 offset:120
	v_lshlrev_b32_e32 v5, 16, v16
	v_fmac_f32_e32 v6, v48, v5
	v_add_f32_e32 v4, v4, v6
	v_and_b32_e32 v6, 0xffff0000, v17
	v_lshlrev_b32_e32 v5, 16, v17
	s_waitcnt lgkmcnt(0)
	v_mul_f32_e32 v3, v3, v6
	v_fmac_f32_e32 v3, v2, v5
	v_add_f32_e32 v2, v4, v3
	v_and_b32_e32 v4, 64, v251
	v_xor_b32_e32 v3, 1, v251
	v_add_u32_e32 v4, 64, v4
	v_cmp_lt_i32_e32 vcc, v3, v4
	ds_write_b128 v185, v[14:17] offset:48
	s_nop 0
	v_cndmask_b32_e32 v3, v251, v3, vcc
	v_lshlrev_b32_e32 v225, 2, v3
	ds_bpermute_b32 v3, v225, v2
	s_waitcnt lgkmcnt(0)
	v_add_f32_e32 v2, v2, v3
	v_xor_b32_e32 v3, 2, v251
	v_cmp_lt_i32_e32 vcc, v3, v4
	s_nop 1
	v_cndmask_b32_e32 v3, v251, v3, vcc
	v_lshlrev_b32_e32 v226, 2, v3
	ds_bpermute_b32 v3, v226, v2
	s_and_saveexec_b64 s[76:77], s[72:73]
	s_cbranch_execz .LBB0_938
	s_waitcnt lgkmcnt(0)
	v_add_f32_e32 v2, v2, v3
	ds_write_b32 v0, v2

; __device__ __forceinline__ unsigned cvt_pk_bf16(float lo, float hi) { unsigned r; asm volatile("v_cvt_pk_bf16_f32 %0, %1, %2" : "=v"(r) : "v"(lo), "v"(hi)); return r; }
; __device__ __forceinline__ float bf_lo(unsigned w) { return __uint_as_float(w << 16); }
; __device__ __forceinline__ float bf_hi(unsigned w) { return __uint_as_float(w & 0xffff0000u); }
; __device__ __forceinline__ void spatial_phase(int j, const bf16_t* UG, bf16_t* Y, const bf16_t* Vt, LAS unsigned char* lds, int sw, View vw) {
;     ...
;             const float* bsp = abs_ + g * 128;
;             const f32x4 gm0 = *(const f32x4*)(gamma + ch0 + 8 * fq), gm1 = *(const f32x4*)(gamma + ch0 + 8 * fq + 4);
; #pragma unroll
;             for (int i = 0; i < 8; ++i) { const int t = 16 * i + fr; const float m2 = M2c[t], bs = bsp[t];
;                 const u32x4 u4 = ug[i];
;                 const float y0 = bf_lo(u4.x) * (gm0[0] * (acc[0][i][0] - m2) + bs), y1 = bf_hi(u4.x) * (gm0[1] * (acc[0][i][1] - m2) + bs);
;                 const float y2 = bf_lo(u4.y) * (gm0[2] * (acc[0][i][2] - m2) + bs), y3 = bf_hi(u4.y) * (gm0[3] * (acc[0][i][3] - m2) + bs);
;                 const float y4 = bf_lo(u4.z) * (gm1[0] * (acc[1][i][0] - m2) + bs), y5 = bf_hi(u4.z) * (gm1[1] * (acc[1][i][1] - m2) + bs);
;                 const float y6 = bf_lo(u4.w) * (gm1[2] * (acc[1][i][2] - m2) + bs), y7 = bf_hi(u4.w) * (gm1[3] * (acc[1][i][3] - m2) + bs);
;                 u32x4 w; w.x = cvt_pk_bf16(y0, y1); w.y = cvt_pk_bf16(y2, y3); w.z = cvt_pk_bf16(y4, y5); w.w = cvt_pk_bf16(y6, y7);
;                 *(u32x4*)(yp + (size_t)(16 * i) * E + ulo) = w; }
;             __syncthreads();
;         }
.LBB0_939:
	s_nop 1
	s_nop 0
	v_lshl_add_u32 v227, s95, 9, v224
	ds_read_b32 v228, v227
	v_lshlrev_b32_e32 v230, 16, v110
	v_and_b32_e32 v110, 0xffff0000, v110
	v_lshl_add_u64 v[166:167], v[156:157], 0, s[76:77]
	s_mov_b32 s82, 0x16000000
	s_waitcnt lgkmcnt(0)
	v_sub_f32_e32 v135, v135, v228
	v_sub_f32_e32 v136, v136, v228
	v_sub_f32_e32 v131, v131, v228
	v_sub_f32_e32 v132, v132, v228
	v_sub_f32_e32 v130, v130, v228
	v_sub_f32_e32 v134, v134, v228
	s_add_i32 s5, s5, 1
	s_add_u32 s76, s76, 0x200
	s_addc_u32 s77, s77, 0
	v_lshl_add_u64 v[164:165], v[164:165], 0, s[96:97]
	v_lshl_add_u64 v[162:163], v[162:163], 0, s[96:97]
	s_cmpk_eq_i32 s76, 0x1000
	v_fma_f32 v135, v247, v135, v231
	v_mul_f32_e32 v110, v135, v110
	v_lshlrev_b32_e32 v135, 16, v111
	v_fma_f32 v136, v248, v136, v231
	v_mul_f32_e32 v135, v136, v135
	v_sub_f32_e32 v136, v137, v228
	v_and_b32_e32 v111, 0xffff0000, v111
	v_fma_f32 v136, v249, v136, v231
	v_mul_f32_e32 v111, v136, v111
	v_lshlrev_b32_e32 v136, 16, v112
	v_and_b32_e32 v112, 0xffff0000, v112
	v_fma_f32 v131, v241, v131, v231
	v_mul_f32_e32 v112, v131, v112
	v_lshlrev_b32_e32 v131, 16, v113
	v_fma_f32 v132, v242, v132, v231
	v_fma_f32 v130, v240, v130, v231
	v_mul_f32_e32 v131, v132, v131
	v_sub_f32_e32 v132, v133, v228
	v_fma_f32 v134, v246, v134, v231
	v_mul_f32_e32 v130, v130, v136
	v_and_b32_e32 v113, 0xffff0000, v113
	v_fmac_f32_e32 v231, v243, v132
	v_mul_f32_e32 v134, v134, v230
	v_mul_f32_e32 v113, v231, v113
	v_cvt_pk_bf16_f32 v110, v134, v110
	v_cvt_pk_bf16_f32 v111, v135, v111
	v_cvt_pk_bf16_f32 v112, v130, v112
	v_add_co_u32_e32 v130, vcc, s82, v166
	v_cvt_pk_bf16_f32 v113, v131, v113
	s_mov_b32 s82, 0x16010000
	s_nop 0
	v_addc_co_u32_e32 v131, vcc, 0, v167, vcc
	global_store_dwordx4 v[130:131], v[110:113], off
	s_nop 0
	ds_read_b32 v110, v227 offset:64
	v_lshlrev_b32_e32 v112, 16, v98
	v_and_b32_e32 v98, 0xffff0000, v98
	s_waitcnt lgkmcnt(0)
	v_sub_f32_e32 v113, v126, v110
	v_sub_f32_e32 v126, v128, v110
	v_sub_f32_e32 v123, v123, v110
	v_sub_f32_e32 v122, v122, v110
	v_sub_f32_e32 v124, v124, v110
	v_fma_f32 v113, v246, v113, v232
	v_mul_f32_e32 v112, v113, v112
	v_sub_f32_e32 v113, v127, v110
	v_fma_f32 v113, v247, v113, v232
	v_mul_f32_e32 v98, v113, v98
	v_lshlrev_b32_e32 v113, 16, v99
	v_fma_f32 v126, v248, v126, v232
	v_mul_f32_e32 v113, v126, v113
	v_sub_f32_e32 v126, v129, v110
	v_and_b32_e32 v99, 0xffff0000, v99
	v_fma_f32 v126, v249, v126, v232
	v_mul_f32_e32 v99, v126, v99
	v_lshlrev_b32_e32 v126, 16, v100
	v_and_b32_e32 v100, 0xffff0000, v100
	v_fma_f32 v123, v241, v123, v232
	v_sub_f32_e32 v110, v125, v110
	v_fma_f32 v122, v240, v122, v232
	v_mul_f32_e32 v100, v123, v100
	v_lshlrev_b32_e32 v123, 16, v101
	v_fma_f32 v124, v242, v124, v232
	v_and_b32_e32 v101, 0xffff0000, v101
	v_fmac_f32_e32 v232, v243, v110
	v_add_co_u32_e32 v110, vcc, s82, v166
	v_mul_f32_e32 v101, v232, v101
	s_nop 0
	v_addc_co_u32_e32 v111, vcc, 0, v167, vcc
	v_mul_f32_e32 v122, v122, v126
	v_mul_f32_e32 v123, v124, v123
	v_cvt_pk_bf16_f32 v98, v112, v98
	v_cvt_pk_bf16_f32 v99, v113, v99
	v_cvt_pk_bf16_f32 v100, v122, v100
	v_cvt_pk_bf16_f32 v101, v123, v101
	global_store_dwordx4 v[110:111], v[98:101], off
	s_nop 0
	ds_read_b32 v98, v227 offset:128
	v_lshlrev_b32_e32 v100, 16, v86
	v_and_b32_e32 v86, 0xffff0000, v86
	s_mov_b32 s82, 0x16020000
	s_waitcnt lgkmcnt(0)
	v_sub_f32_e32 v101, v118, v98
	v_sub_f32_e32 v110, v120, v98
	v_sub_f32_e32 v111, v114, v98
	v_sub_f32_e32 v112, v116, v98
	v_fma_f32 v101, v246, v101, v233
	v_mul_f32_e32 v100, v101, v100
	v_sub_f32_e32 v101, v119, v98
	v_fma_f32 v101, v247, v101, v233
	v_mul_f32_e32 v86, v101, v86
	v_lshlrev_b32_e32 v101, 16, v87
	v_fma_f32 v110, v248, v110, v233
	v_mul_f32_e32 v101, v110, v101
	v_sub_f32_e32 v110, v121, v98
	v_and_b32_e32 v87, 0xffff0000, v87
	v_fma_f32 v110, v249, v110, v233
	v_mul_f32_e32 v87, v110, v87
	v_lshlrev_b32_e32 v110, 16, v88
	v_fma_f32 v111, v240, v111, v233
	v_mul_f32_e32 v110, v111, v110
	v_sub_f32_e32 v111, v115, v98
	v_and_b32_e32 v88, 0xffff0000, v88
	v_fma_f32 v111, v241, v111, v233
	v_sub_f32_e32 v98, v117, v98
	v_mul_f32_e32 v88, v111, v88
	v_lshlrev_b32_e32 v111, 16, v89
	v_fma_f32 v112, v242, v112, v233
	v_and_b32_e32 v89, 0xffff0000, v89
	v_fmac_f32_e32 v233, v243, v98
	v_add_co_u32_e32 v98, vcc, s82, v166
	v_mul_f32_e32 v89, v233, v89
	s_nop 0
	v_addc_co_u32_e32 v99, vcc, 0, v167, vcc
	v_mul_f32_e32 v111, v112, v111
	v_cvt_pk_bf16_f32 v86, v100, v86
	v_cvt_pk_bf16_f32 v87, v101, v87
	v_cvt_pk_bf16_f32 v88, v110, v88
	v_cvt_pk_bf16_f32 v89, v111, v89
	global_store_dwordx4 v[98:99], v[86:89], off
	s_nop 0
	ds_read_b32 v86, v227 offset:192
	v_lshlrev_b32_e32 v88, 16, v70
	v_and_b32_e32 v70, 0xffff0000, v70
	s_mov_b32 s82, 0x16030000
	s_waitcnt lgkmcnt(0)
	v_sub_f32_e32 v89, v106, v86
	v_sub_f32_e32 v98, v108, v86
	v_sub_f32_e32 v99, v102, v86
	v_sub_f32_e32 v100, v104, v86
	v_fma_f32 v89, v246, v89, v234
	v_mul_f32_e32 v88, v89, v88
	v_sub_f32_e32 v89, v107, v86
	v_fma_f32 v89, v247, v89, v234
	v_mul_f32_e32 v70, v89, v70
	v_lshlrev_b32_e32 v89, 16, v71
	v_fma_f32 v98, v248, v98, v234
	v_mul_f32_e32 v89, v98, v89
	v_sub_f32_e32 v98, v109, v86
	v_and_b32_e32 v71, 0xffff0000, v71
	v_fma_f32 v98, v249, v98, v234
	v_mul_f32_e32 v71, v98, v71
	v_lshlrev_b32_e32 v98, 16, v72
	v_fma_f32 v99, v240, v99, v234
	v_mul_f32_e32 v98, v99, v98
	v_sub_f32_e32 v99, v103, v86
	v_and_b32_e32 v72, 0xffff0000, v72
	v_fma_f32 v99, v241, v99, v234
	v_sub_f32_e32 v86, v105, v86
	v_mul_f32_e32 v72, v99, v72
	v_lshlrev_b32_e32 v99, 16, v73
	v_fma_f32 v100, v242, v100, v234
	v_and_b32_e32 v73, 0xffff0000, v73
	v_fmac_f32_e32 v234, v243, v86
	v_add_co_u32_e32 v86, vcc, s82, v166
	v_mul_f32_e32 v73, v234, v73
	s_nop 0
	v_addc_co_u32_e32 v87, vcc, 0, v167, vcc
	v_mul_f32_e32 v99, v100, v99
	v_cvt_pk_bf16_f32 v70, v88, v70
	v_cvt_pk_bf16_f32 v71, v89, v71
	v_cvt_pk_bf16_f32 v72, v98, v72
	v_cvt_pk_bf16_f32 v73, v99, v73
	global_store_dwordx4 v[86:87], v[70:73], off
	s_nop 0
	ds_read_b32 v70, v227 offset:256
	v_lshlrev_b32_e32 v72, 16, v50
	v_and_b32_e32 v50, 0xffff0000, v50
	s_mov_b32 s82, 0x16040000
	s_waitcnt lgkmcnt(0)
; __device__ __forceinline__ unsigned cvt_pk_bf16(float lo, float hi) { unsigned r; asm volatile("v_cvt_pk_bf16_f32 %0, %1, %2" : "=v"(r) : "v"(lo), "v"(hi)); return r; }
; __device__ __forceinline__ float bf_lo(unsigned w) { return __uint_as_float(w << 16); }
; __device__ __forceinline__ float bf_hi(unsigned w) { return __uint_as_float(w & 0xffff0000u); }
; __device__ __forceinline__ void spatial_phase(int j, const bf16_t* UG, bf16_t* Y, const bf16_t* Vt, LAS unsigned char* lds, int sw, View vw) {
;     ...
;             for (int i = 0; i < 8; ++i) { const int t = 16 * i + fr; const float m2 = M2c[t], bs = bsp[t];
;                 const u32x4 u4 = ug[i];
;                 const float y0 = bf_lo(u4.x) * (gm0[0] * (acc[0][i][0] - m2) + bs), y1 = bf_hi(u4.x) * (gm0[1] * (acc[0][i][1] - m2) + bs);
;                 const float y2 = bf_lo(u4.y) * (gm0[2] * (acc[0][i][2] - m2) + bs), y3 = bf_hi(u4.y) * (gm0[3] * (acc[0][i][3] - m2) + bs);
;                 const float y4 = bf_lo(u4.z) * (gm1[0] * (acc[1][i][0] - m2) + bs), y5 = bf_hi(u4.z) * (gm1[1] * (acc[1][i][1] - m2) + bs);
;                 const float y6 = bf_lo(u4.w) * (gm1[2] * (acc[1][i][2] - m2) + bs), y7 = bf_hi(u4.w) * (gm1[3] * (acc[1][i][3] - m2) + bs);
;                 u32x4 w; w.x = cvt_pk_bf16(y0, y1); w.y = cvt_pk_bf16(y2, y3); w.z = cvt_pk_bf16(y4, y5); w.w = cvt_pk_bf16(y6, y7);
;                 *(u32x4*)(yp + (size_t)(16 * i) * E + ulo) = w; }
;             __syncthreads();
;         }
;     }
	v_sub_f32_e32 v73, v94, v70
	v_sub_f32_e32 v86, v96, v70
	v_sub_f32_e32 v87, v90, v70
	v_sub_f32_e32 v88, v92, v70
	v_fma_f32 v73, v246, v73, v235
	v_mul_f32_e32 v72, v73, v72
	v_sub_f32_e32 v73, v95, v70
	v_fma_f32 v73, v247, v73, v235
	v_mul_f32_e32 v50, v73, v50
	v_lshlrev_b32_e32 v73, 16, v51
	v_fma_f32 v86, v248, v86, v235
	v_mul_f32_e32 v73, v86, v73
	v_sub_f32_e32 v86, v97, v70
	v_and_b32_e32 v51, 0xffff0000, v51
	v_fma_f32 v86, v249, v86, v235
	v_mul_f32_e32 v51, v86, v51
	v_lshlrev_b32_e32 v86, 16, v52
	v_fma_f32 v87, v240, v87, v235
	v_mul_f32_e32 v86, v87, v86
	v_sub_f32_e32 v87, v91, v70
	v_and_b32_e32 v52, 0xffff0000, v52
	v_fma_f32 v87, v241, v87, v235
	v_sub_f32_e32 v70, v93, v70
	v_mul_f32_e32 v52, v87, v52
	v_lshlrev_b32_e32 v87, 16, v53
	v_fma_f32 v88, v242, v88, v235
	v_and_b32_e32 v53, 0xffff0000, v53
	v_fmac_f32_e32 v235, v243, v70
	v_add_co_u32_e32 v70, vcc, s82, v166
	v_mul_f32_e32 v53, v235, v53
	s_nop 0
	v_addc_co_u32_e32 v71, vcc, 0, v167, vcc
	v_mul_f32_e32 v87, v88, v87
	v_cvt_pk_bf16_f32 v50, v72, v50
	v_cvt_pk_bf16_f32 v51, v73, v51
	v_cvt_pk_bf16_f32 v52, v86, v52
	v_cvt_pk_bf16_f32 v53, v87, v53
	global_store_dwordx4 v[70:71], v[50:53], off
	s_nop 0
	ds_read_b32 v50, v227 offset:320
	v_lshlrev_b32_e32 v52, 16, v42
	v_and_b32_e32 v42, 0xffff0000, v42
	s_mov_b32 s82, 0x16050000
	s_waitcnt lgkmcnt(0)
	v_sub_f32_e32 v53, v82, v50
	v_sub_f32_e32 v70, v84, v50
	v_sub_f32_e32 v71, v78, v50
	v_sub_f32_e32 v72, v80, v50
	v_fma_f32 v53, v246, v53, v236
	v_mul_f32_e32 v52, v53, v52
	v_sub_f32_e32 v53, v83, v50
	v_fma_f32 v53, v247, v53, v236
	v_mul_f32_e32 v42, v53, v42
	v_lshlrev_b32_e32 v53, 16, v43
	v_fma_f32 v70, v248, v70, v236
	v_mul_f32_e32 v53, v70, v53
	v_sub_f32_e32 v70, v85, v50
	v_and_b32_e32 v43, 0xffff0000, v43
	v_fma_f32 v70, v249, v70, v236
	v_mul_f32_e32 v43, v70, v43
	v_lshlrev_b32_e32 v70, 16, v44
	v_fma_f32 v71, v240, v71, v236
	v_mul_f32_e32 v70, v71, v70
	v_sub_f32_e32 v71, v79, v50
	v_and_b32_e32 v44, 0xffff0000, v44
	v_fma_f32 v71, v241, v71, v236
	v_sub_f32_e32 v50, v81, v50
	v_mul_f32_e32 v44, v71, v44
	v_lshlrev_b32_e32 v71, 16, v45
	v_fma_f32 v72, v242, v72, v236
	v_and_b32_e32 v45, 0xffff0000, v45
	v_fmac_f32_e32 v236, v243, v50
	v_add_co_u32_e32 v50, vcc, s82, v166
	v_mul_f32_e32 v45, v236, v45
	s_nop 0
	v_addc_co_u32_e32 v51, vcc, 0, v167, vcc
	v_mul_f32_e32 v71, v72, v71
	v_cvt_pk_bf16_f32 v42, v52, v42
	v_cvt_pk_bf16_f32 v43, v53, v43
	v_cvt_pk_bf16_f32 v44, v70, v44
	v_cvt_pk_bf16_f32 v45, v71, v45
	global_store_dwordx4 v[50:51], v[42:45], off
	s_nop 0
	ds_read_b32 v42, v227 offset:384
	v_lshlrev_b32_e32 v44, 16, v38
	v_and_b32_e32 v38, 0xffff0000, v38
	s_mov_b32 s82, 0x16060000
	s_waitcnt lgkmcnt(0)
	v_sub_f32_e32 v45, v74, v42
	v_sub_f32_e32 v50, v76, v42
	v_sub_f32_e32 v51, v66, v42
	v_sub_f32_e32 v52, v68, v42
	v_fma_f32 v45, v246, v45, v237
	v_mul_f32_e32 v44, v45, v44
	v_sub_f32_e32 v45, v75, v42
	v_fma_f32 v45, v247, v45, v237
	v_mul_f32_e32 v38, v45, v38
	v_lshlrev_b32_e32 v45, 16, v39
	v_fma_f32 v50, v248, v50, v237
	v_mul_f32_e32 v45, v50, v45
	v_sub_f32_e32 v50, v77, v42
	v_and_b32_e32 v39, 0xffff0000, v39
	v_fma_f32 v50, v249, v50, v237
	v_mul_f32_e32 v39, v50, v39
	v_lshlrev_b32_e32 v50, 16, v40
	v_fma_f32 v51, v240, v51, v237
	v_mul_f32_e32 v50, v51, v50
	v_sub_f32_e32 v51, v67, v42
	v_and_b32_e32 v40, 0xffff0000, v40
	v_fma_f32 v51, v241, v51, v237
	v_sub_f32_e32 v42, v69, v42
	v_mul_f32_e32 v40, v51, v40
	v_lshlrev_b32_e32 v51, 16, v41
	v_fma_f32 v52, v242, v52, v237
	v_and_b32_e32 v41, 0xffff0000, v41
	v_fmac_f32_e32 v237, v243, v42
	v_add_co_u32_e32 v42, vcc, s82, v166
	v_mul_f32_e32 v41, v237, v41
	s_nop 0
	v_addc_co_u32_e32 v43, vcc, 0, v167, vcc
	v_mul_f32_e32 v51, v52, v51
	v_cvt_pk_bf16_f32 v38, v44, v38
	v_cvt_pk_bf16_f32 v39, v45, v39
	v_cvt_pk_bf16_f32 v40, v50, v40
	v_cvt_pk_bf16_f32 v41, v51, v41
	global_store_dwordx4 v[42:43], v[38:41], off
	s_nop 0
	ds_read_b32 v38, v227 offset:448
	v_lshlrev_b32_e32 v40, 16, v34
	v_and_b32_e32 v34, 0xffff0000, v34
	s_mov_b32 s82, 0x16070000
	s_waitcnt lgkmcnt(0)
	v_sub_f32_e32 v41, v58, v38
	v_sub_f32_e32 v42, v60, v38
	v_sub_f32_e32 v43, v46, v38
	v_sub_f32_e32 v44, v48, v38
	v_fma_f32 v41, v246, v41, v238
	v_mul_f32_e32 v40, v41, v40
	v_sub_f32_e32 v41, v59, v38
	v_fma_f32 v41, v247, v41, v238
	v_mul_f32_e32 v34, v41, v34
	v_lshlrev_b32_e32 v41, 16, v35
	v_fma_f32 v42, v248, v42, v238
	v_mul_f32_e32 v41, v42, v41
	v_sub_f32_e32 v42, v61, v38
	v_and_b32_e32 v35, 0xffff0000, v35
	v_fma_f32 v42, v249, v42, v238
	v_mul_f32_e32 v35, v42, v35
	v_lshlrev_b32_e32 v42, 16, v36
	v_fma_f32 v43, v240, v43, v238
	v_mul_f32_e32 v42, v43, v42
	v_sub_f32_e32 v43, v47, v38
	v_and_b32_e32 v36, 0xffff0000, v36
	v_fma_f32 v43, v241, v43, v238
	v_sub_f32_e32 v38, v49, v38
	v_mul_f32_e32 v36, v43, v36
	v_lshlrev_b32_e32 v43, 16, v37
	v_fma_f32 v44, v242, v44, v238
	v_and_b32_e32 v37, 0xffff0000, v37
	v_fmac_f32_e32 v238, v243, v38
	v_add_co_u32_e32 v38, vcc, s82, v166
	s_mov_b64 s[82:83], 0x400
	v_mul_f32_e32 v37, v238, v37
	v_addc_co_u32_e32 v39, vcc, 0, v167, vcc
	v_lshl_add_u64 v[160:161], v[160:161], 0, s[82:83]
	v_mul_f32_e32 v43, v44, v43
	v_cvt_pk_bf16_f32 v34, v40, v34
	v_cvt_pk_bf16_f32 v35, v41, v35
	v_cvt_pk_bf16_f32 v36, v42, v36
	v_cvt_pk_bf16_f32 v37, v43, v37
	global_store_dwordx4 v[38:39], v[34:37], off
	s_barrier
	s_cbranch_scc1 .LBB0_869
; #define LAS __attribute__((address_space(3)))
; __device__ __forceinline__ void build_wp(const float* wsrc_g, LAS unsigned char* WPb, LAS float* M2b, const LAS float* MU, const LAS float* RS, int tid) {
;     const int t = tid >> 2, part = tid & 3, s0 = 32 * part;
;     const float* wsrc = wsrc_g + t * 128 + s0;
;     float m2 = 0.f;
; #pragma unroll
; __device__ __forceinline__ void spatial_phase(int j, const bf16_t* UG, bf16_t* Y, const bf16_t* Vt, LAS unsigned char* lds, int sw, View vw) {
;     ...
;         for (int g = 0; g < 8; ++g) {
;             const int buf = g & 1, ch0 = 256 * g + 32 * wave;
;             const bf16_t* up = UG + (size_t)tok0 * E + ch0; bf16_t* yp = Y + (size_t)tok0 * E + ch0;
; #pragma unroll
;             for (int i = 0; i < 8; ++i) ug[i] = ntload((const u32x4*)(up + (size_t)(16 * i) * E + ulo));
;             if (g < 7) {
;                 build_wp(aws + (size_t)(g + 1) * 128 * 128, lds + (buf ^ 1) * WPB, M2 + (buf ^ 1) * 128, MU, RS, tid);
;             }
;             const LAS unsigned char* WP = lds + buf * WPB; const LAS float* M2c = M2 + buf * 128;
;             f32x4 acc[2][8];
; #pragma unroll
;             for (int f = 0; f < 2; ++f)
; #pragma unroll
;                 for (int i = 0; i < 8; ++i) acc[f][i] = (f32x4){0.f, 0.f, 0.f, 0.f};
; #pragma unroll
;             for (int i = 0; i < 8; ++i)
; #pragma unroll
;                 for (int ks = 0; ks <= (i >> 1); ++ks) {
;                     const bf16x8 wf = *(const LAS bf16x8*)(WP + (16 * i + fr) * WPITCH + (32 * ks + 8 * fq) * 2);
; #pragma unroll
;                     for (int f = 0; f < 2; ++f) acc[f][i] = __builtin_amdgcn_mfma_f32_16x16x32_bf16(vf[f][ks], wf, acc[f][i], 0, 0, 0);
;                 }
;             if (g < 7) {
;                 const bf16_t* vp = Vt + ((size_t)chunk * E + ch0 + 256) * 128;
; #pragma unroll
;                 for (int f = 0; f < 2; ++f)
; #pragma unroll
;                     for (int ks = 0; ks < 4; ++ks) vf[f][ks] = ntload((const bf16x8*)(vp + (4 * f) * 128 + 32 * ks + vlo));
;             }
;             const float* bsp = abs_ + g * 128;
;             const f32x4 gm0 = *(const f32x4*)(gamma + ch0 + 8 * fq), gm1 = *(const f32x4*)(gamma + ch0 + 8 * fq + 4);
; #pragma unroll
;             for (int i = 0; i < 8; ++i) { const int t = 16 * i + fr; const float m2 = M2c[t], bs = bsp[t];
.LBB0_940:
	v_lshl_add_u64 v[168:169], v[142:143], 0, s[76:77]
	global_load_dwordx4 v[240:243], v[160:161], off
	global_load_dwordx4 v[246:249], v[160:161], off offset:-16
	global_load_dword v231, v[168:169], off
	global_load_dword v232, v[168:169], off offset:64
	global_load_dword v233, v[168:169], off offset:128
	global_load_dword v234, v[168:169], off offset:192
	global_load_dword v235, v[168:169], off offset:256
	global_load_dword v236, v[168:169], off offset:320
	global_load_dword v237, v[168:169], off offset:384
	global_load_dword v238, v[168:169], off offset:448
	s_cmpk_eq_i32 s76, 0xe00
	s_cbranch_scc1 .Lsp_top_noWs
	global_load_dwordx4 v[186:189], v[164:165], off offset:-64
	global_load_dwordx4 v[190:193], v[164:165], off offset:-48
	global_load_dwordx4 v[194:197], v[164:165], off offset:-32
	global_load_dwordx4 v[198:201], v[164:165], off offset:-16
	global_load_dwordx4 v[202:205], v[164:165], off
	global_load_dwordx4 v[206:209], v[164:165], off offset:16
	global_load_dwordx4 v[210:213], v[164:165], off offset:32
	global_load_dwordx4 v[214:217], v[164:165], off offset:48
.Lsp_top_noWs:
	s_lshl_b64 s[82:83], s[76:77], 7
	v_lshl_add_u64 v[34:35], v[158:159], 0, s[82:83]
	v_add_co_u32_e32 v36, vcc, 0x6000000, v34
	s_and_b32 s95, s5, 1
	s_nop 0
	v_addc_co_u32_e32 v37, vcc, 0, v35, vcc
	v_add_co_u32_e32 v38, vcc, 0x6000400, v34
	s_cmpk_lg_i32 s76, 0xe00
	s_nop 0
	v_addc_co_u32_e32 v39, vcc, 0, v35, vcc
	global_load_dwordx4 v[110:113], v[36:37], off nt
	global_load_dwordx4 v[98:101], v[38:39], off nt
	v_add_co_u32_e32 v36, vcc, 0x6000800, v34
	s_nop 1
	v_addc_co_u32_e32 v37, vcc, 0, v35, vcc
	v_add_co_u32_e32 v38, vcc, 0x6000c00, v34
	s_nop 1
	v_addc_co_u32_e32 v39, vcc, 0, v35, vcc
	global_load_dwordx4 v[86:89], v[36:37], off nt
	global_load_dwordx4 v[70:73], v[38:39], off nt
	v_add_co_u32_e32 v36, vcc, 0x6001000, v34
	s_nop 1
	v_addc_co_u32_e32 v37, vcc, 0, v35, vcc
	v_add_co_u32_e32 v38, vcc, 0x6001400, v34
	s_nop 1
	v_addc_co_u32_e32 v39, vcc, 0, v35, vcc
	global_load_dwordx4 v[50:53], v[36:37], off nt
	global_load_dwordx4 v[42:45], v[38:39], off nt
	v_add_co_u32_e32 v36, vcc, 0x6001800, v34
	s_nop 1
	v_addc_co_u32_e32 v37, vcc, 0, v35, vcc
	v_add_co_u32_e32 v34, vcc, 0x6001c00, v34
	s_nop 1
	v_addc_co_u32_e32 v35, vcc, 0, v35, vcc
	global_load_dwordx4 v[38:41], v[36:37], off nt
	s_nop 0
	global_load_dwordx4 v[34:37], v[34:35], off nt
	s_cselect_b64 vcc, -1, 0
	s_cmpk_eq_i32 s76, 0xe00
	s_cbranch_scc1 .LBB0_1008
	s_waitcnt vmcnt(8)
	v_mov_b32_e32 v58, 0
	v_mov_b32_e32 v59, 0
	s_and_saveexec_b64 s[92:93], s[6:7]
	s_cbranch_execz .LBB0_943
	ds_read_b32 v59, v173
	s_waitcnt lgkmcnt(0)
	v_mul_f32_e32 v59, v186, v59
.LBB0_943:
	s_or_b64 exec, exec, s[92:93]
	s_and_saveexec_b64 s[92:93], s[8:9]
	s_cbranch_execz .LBB0_945
	ds_read_b32 v46, v173 offset:4
	s_waitcnt lgkmcnt(0)
	v_mul_f32_e32 v58, v187, v46
.LBB0_945:
	s_or_b64 exec, exec, s[92:93]
	v_cvt_pk_bf16_f32 v46, v59, v58
	ds_read_b64 v[68:69], v175
	v_mov_b32_e32 v47, 0
	v_mov_b32_e32 v58, 0
	s_and_saveexec_b64 s[92:93], s[10:11]
	s_cbranch_execz .LBB0_947
	ds_read_b32 v58, v173 offset:8
	s_waitcnt lgkmcnt(0)
	v_mul_f32_e32 v58, v188, v58
.LBB0_947:
	s_or_b64 exec, exec, s[92:93]
	s_and_saveexec_b64 s[92:93], s[12:13]
	s_cbranch_execz .LBB0_949
	ds_read_b32 v47, v173 offset:12
	s_waitcnt lgkmcnt(0)
	v_mul_f32_e32 v47, v189, v47
.LBB0_949:
	s_or_b64 exec, exec, s[92:93]
	v_cvt_pk_bf16_f32 v47, v58, v47
	ds_read_b64 v[78:79], v175 offset:8
	v_mov_b32_e32 v48, 0
	v_mov_b32_e32 v49, 0
	s_and_saveexec_b64 s[92:93], s[14:15]
	s_cbranch_execz .LBB0_951
	ds_read_b32 v49, v173 offset:16
	s_waitcnt lgkmcnt(0)
	v_mul_f32_e32 v49, v190, v49
.LBB0_951:
	s_or_b64 exec, exec, s[92:93]
	s_and_saveexec_b64 s[92:93], s[16:17]
	s_cbranch_execz .LBB0_953
	ds_read_b32 v48, v173 offset:20
	s_waitcnt lgkmcnt(0)
	v_mul_f32_e32 v48, v191, v48
.LBB0_953:
	s_or_b64 exec, exec, s[92:93]
	v_cvt_pk_bf16_f32 v48, v49, v48
	ds_read_b64 v[80:81], v175 offset:16
	v_mov_b32_e32 v49, 0
	v_mov_b32_e32 v54, 0
	s_and_saveexec_b64 s[92:93], s[18:19]
	s_cbranch_execz .LBB0_955
	ds_read_b32 v54, v173 offset:24
	s_waitcnt lgkmcnt(0)
	v_mul_f32_e32 v54, v192, v54
.LBB0_955:
	s_or_b64 exec, exec, s[92:93]
	s_and_saveexec_b64 s[92:93], s[20:21]
	s_cbranch_execz .LBB0_957
	ds_read_b32 v49, v173 offset:28
	s_waitcnt lgkmcnt(0)
	v_mul_f32_e32 v49, v193, v49
.LBB0_957:
	s_or_b64 exec, exec, s[92:93]
	v_cvt_pk_bf16_f32 v49, v54, v49
	ds_read_b64 v[82:83], v175 offset:24
	s_xor_b32 s89, s95, 1
	s_mul_i32 s82, s89, 0x8800
	v_add_u32_e32 v114, s82, v185
	v_mov_b32_e32 v54, 0
	v_mov_b32_e32 v55, 0
	ds_write_b128 v114, v[46:49]
	s_and_saveexec_b64 s[92:93], s[22:23]
	s_cbranch_execz .LBB0_959
	ds_read_b32 v55, v173 offset:32
	s_waitcnt lgkmcnt(0)
	v_mul_f32_e32 v55, v194, v55
.LBB0_959:
	s_or_b64 exec, exec, s[92:93]
	s_and_saveexec_b64 s[92:93], s[24:25]
	s_cbranch_execz .LBB0_961
	ds_read_b32 v54, v173 offset:36
	s_waitcnt lgkmcnt(0)
	v_mul_f32_e32 v54, v195, v54
.LBB0_961:
	s_or_b64 exec, exec, s[92:93]
	v_cvt_pk_bf16_f32 v54, v55, v54
	ds_read_b64 v[84:85], v175 offset:32
	v_mov_b32_e32 v55, 0
	v_mov_b32_e32 v60, 0
	s_and_saveexec_b64 s[92:93], s[26:27]
	s_cbranch_execz .LBB0_963
	ds_read_b32 v60, v173 offset:40
	s_waitcnt lgkmcnt(0)
	v_mul_f32_e32 v60, v196, v60
.LBB0_963:
	s_or_b64 exec, exec, s[92:93]
	s_and_saveexec_b64 s[92:93], s[28:29]
	s_cbranch_execz .LBB0_965
	ds_read_b32 v55, v173 offset:44
	s_waitcnt lgkmcnt(0)
	v_mul_f32_e32 v55, v197, v55
.LBB0_965:
	s_or_b64 exec, exec, s[92:93]
	v_cvt_pk_bf16_f32 v55, v60, v55
	ds_read_b64 v[90:91], v175 offset:40
	v_mov_b32_e32 v60, 0
	v_mov_b32_e32 v61, 0
	s_and_saveexec_b64 s[92:93], s[30:31]
	s_cbranch_execz .LBB0_967
	ds_read_b32 v61, v173 offset:48
	s_waitcnt lgkmcnt(0)
	v_mul_f32_e32 v61, v198, v61
; #define LAS __attribute__((address_space(3)))
; __device__ __forceinline__ unsigned cvt_pk_bf16(float lo, float hi) { unsigned r; asm volatile("v_cvt_pk_bf16_f32 %0, %1, %2" : "=v"(r) : "v"(lo), "v"(hi)); return r; }
; __device__ __forceinline__ float bf_lo(unsigned w) { return __uint_as_float(w << 16); }
; __device__ __forceinline__ float bf_hi(unsigned w) { return __uint_as_float(w & 0xffff0000u); }
; __device__ __forceinline__ void build_wp(const float* wsrc_g, LAS unsigned char* WPb, LAS float* M2b, const LAS float* MU, const LAS float* RS, int tid) {
;     const int t = tid >> 2, part = tid & 3, s0 = 32 * part;
;     const float* wsrc = wsrc_g + t * 128 + s0;
;     float m2 = 0.f;
; #pragma unroll
;     for (int q = 0; q < 4; ++q) { const f32x4 w0 = *(const f32x4*)(wsrc + 8 * q), w1 = *(const f32x4*)(wsrc + 8 * q + 4);
;         const float wv[8] = {w0[0], w0[1], w0[2], w0[3], w1[0], w1[1], w1[2], w1[3]};
;         unsigned pk[4];
; #pragma unroll
;         for (int e = 0; e < 8; e += 2) { const int s = s0 + 8 * q + e;
;             const float x0 = (s <= t) ? wv[e] * RS[s] : 0.f, x1 = (s + 1 <= t) ? wv[e + 1] * RS[s + 1] : 0.f;
;             const unsigned p = cvt_pk_bf16(x0, x1); pk[e >> 1] = p;
;             m2 += bf_lo(p) * MU[s] + bf_hi(p) * MU[s + 1]; }
;         *(LAS u32x4*)(WPb + t * 272 + (s0 + 8 * q) * 2) = (u32x4){pk[0], pk[1], pk[2], pk[3]}; }
.LBB0_967:
	s_or_b64 exec, exec, s[92:93]
	s_and_saveexec_b64 s[92:93], s[34:35]
	s_cbranch_execz .LBB0_969
	ds_read_b32 v56, v173 offset:52
	s_waitcnt lgkmcnt(0)
	v_mul_f32_e32 v60, v199, v56
.LBB0_969:
	s_or_b64 exec, exec, s[92:93]
	v_cvt_pk_bf16_f32 v56, v61, v60
	ds_read_b64 v[92:93], v175 offset:48
	v_mov_b32_e32 v57, 0
	v_mov_b32_e32 v60, 0
	s_and_saveexec_b64 s[92:93], s[36:37]
	s_cbranch_execz .LBB0_971
	ds_read_b32 v60, v173 offset:56
	s_waitcnt lgkmcnt(0)
	v_mul_f32_e32 v60, v200, v60
.LBB0_971:
	s_or_b64 exec, exec, s[92:93]
	s_and_saveexec_b64 s[92:93], s[38:39]
	s_cbranch_execz .LBB0_973
	ds_read_b32 v57, v173 offset:60
	s_waitcnt lgkmcnt(0)
	v_mul_f32_e32 v57, v201, v57
.LBB0_973:
	s_or_b64 exec, exec, s[92:93]
	v_cvt_pk_bf16_f32 v57, v60, v57
	ds_read_b64 v[94:95], v175 offset:56
	v_mov_b32_e32 v58, 0
	v_mov_b32_e32 v59, 0
	ds_write_b128 v114, v[54:57] offset:16
	s_and_saveexec_b64 s[92:93], s[40:41]
	s_cbranch_execz .LBB0_975
	ds_read_b32 v59, v173 offset:64
	s_waitcnt lgkmcnt(0)
	v_mul_f32_e32 v59, v202, v59
.LBB0_975:
	s_or_b64 exec, exec, s[92:93]
	s_and_saveexec_b64 s[92:93], s[42:43]
	s_cbranch_execz .LBB0_977
	ds_read_b32 v58, v173 offset:68
	s_waitcnt lgkmcnt(0)
	v_mul_f32_e32 v58, v203, v58
.LBB0_977:
	s_or_b64 exec, exec, s[92:93]
	v_cvt_pk_bf16_f32 v58, v59, v58
	ds_read_b64 v[96:97], v175 offset:64
	v_mov_b32_e32 v59, 0
	v_mov_b32_e32 v64, 0
	s_and_saveexec_b64 s[92:93], s[44:45]
	s_cbranch_execz .LBB0_979
	ds_read_b32 v64, v173 offset:72
	s_waitcnt lgkmcnt(0)
	v_mul_f32_e32 v64, v204, v64
.LBB0_979:
	s_or_b64 exec, exec, s[92:93]
	s_and_saveexec_b64 s[92:93], s[46:47]
	s_cbranch_execz .LBB0_981
	ds_read_b32 v59, v173 offset:76
	s_waitcnt lgkmcnt(0)
	v_mul_f32_e32 v59, v205, v59
.LBB0_981:
	s_or_b64 exec, exec, s[92:93]
	v_cvt_pk_bf16_f32 v59, v64, v59
	ds_read_b64 v[102:103], v175 offset:72
	v_mov_b32_e32 v64, 0
	v_mov_b32_e32 v65, 0
	s_and_saveexec_b64 s[92:93], s[48:49]
	s_cbranch_execz .LBB0_983
	ds_read_b32 v65, v173 offset:80
	s_waitcnt lgkmcnt(0)
	v_mul_f32_e32 v65, v206, v65
.LBB0_983:
	s_or_b64 exec, exec, s[92:93]
	s_and_saveexec_b64 s[92:93], s[50:51]
	s_cbranch_execz .LBB0_985
	ds_read_b32 v60, v173 offset:84
	s_waitcnt lgkmcnt(0)
	v_mul_f32_e32 v64, v207, v60
.LBB0_985:
	s_or_b64 exec, exec, s[92:93]
	v_cvt_pk_bf16_f32 v60, v65, v64
	ds_read_b64 v[104:105], v175 offset:80
	v_mov_b32_e32 v61, 0
	v_mov_b32_e32 v64, 0
	s_and_saveexec_b64 s[92:93], s[52:53]
	s_cbranch_execz .LBB0_987
	ds_read_b32 v64, v173 offset:88
	s_waitcnt lgkmcnt(0)
	v_mul_f32_e32 v64, v208, v64
.LBB0_987:
	s_or_b64 exec, exec, s[92:93]
	s_and_saveexec_b64 s[92:93], s[54:55]
	s_cbranch_execz .LBB0_989
	ds_read_b32 v61, v173 offset:92
	s_waitcnt lgkmcnt(0)
	v_mul_f32_e32 v61, v209, v61
.LBB0_989:
	s_or_b64 exec, exec, s[92:93]
	v_cvt_pk_bf16_f32 v61, v64, v61
	ds_read_b64 v[106:107], v175 offset:88
	v_mov_b32_e32 v62, 0
	v_mov_b32_e32 v63, 0
	ds_write_b128 v114, v[58:61] offset:32
	s_and_saveexec_b64 s[92:93], s[56:57]
	s_cbranch_execz .LBB0_991
	ds_read_b32 v63, v173 offset:96
	s_waitcnt lgkmcnt(0)
	v_mul_f32_e32 v63, v210, v63
.LBB0_991:
	s_or_b64 exec, exec, s[92:93]
	s_and_saveexec_b64 s[92:93], s[58:59]
	s_cbranch_execz .LBB0_993
	ds_read_b32 v62, v173 offset:100
	s_waitcnt lgkmcnt(0)
	v_mul_f32_e32 v62, v211, v62
.LBB0_993:
	s_or_b64 exec, exec, s[92:93]
	v_cvt_pk_bf16_f32 v62, v63, v62
	ds_read_b64 v[74:75], v175 offset:96
	v_mov_b32_e32 v63, 0
	v_mov_b32_e32 v108, 0
	s_and_saveexec_b64 s[92:93], s[60:61]
	s_cbranch_execz .LBB0_995
	ds_read_b32 v108, v173 offset:104
	s_waitcnt lgkmcnt(0)
	v_mul_f32_e32 v108, v212, v108
.LBB0_995:
	s_or_b64 exec, exec, s[92:93]
	s_and_saveexec_b64 s[92:93], s[62:63]
	s_cbranch_execz .LBB0_997
	ds_read_b32 v63, v173 offset:108
	s_waitcnt lgkmcnt(0)
	v_mul_f32_e32 v63, v213, v63
.LBB0_997:
	s_or_b64 exec, exec, s[92:93]
	v_cvt_pk_bf16_f32 v63, v108, v63
	ds_read_b64 v[76:77], v175 offset:104
	v_mov_b32_e32 v108, 0
	v_mov_b32_e32 v109, 0
	s_and_saveexec_b64 s[92:93], s[64:65]
	s_cbranch_execz .LBB0_999
	ds_read_b32 v109, v173 offset:112
	s_waitcnt lgkmcnt(0)
	v_mul_f32_e32 v109, v214, v109
; #define LAS __attribute__((address_space(3)))
; __device__ __forceinline__ unsigned cvt_pk_bf16(float lo, float hi) { unsigned r; asm volatile("v_cvt_pk_bf16_f32 %0, %1, %2" : "=v"(r) : "v"(lo), "v"(hi)); return r; }
; __device__ __forceinline__ float bf_lo(unsigned w) { return __uint_as_float(w << 16); }
; __device__ __forceinline__ float bf_hi(unsigned w) { return __uint_as_float(w & 0xffff0000u); }
; __device__ __forceinline__ void build_wp(const float* wsrc_g, LAS unsigned char* WPb, LAS float* M2b, const LAS float* MU, const LAS float* RS, int tid) {
;     ...
;     for (int q = 0; q < 4; ++q) { const f32x4 w0 = *(const f32x4*)(wsrc + 8 * q), w1 = *(const f32x4*)(wsrc + 8 * q + 4);
;         const float wv[8] = {w0[0], w0[1], w0[2], w0[3], w1[0], w1[1], w1[2], w1[3]};
;         unsigned pk[4];
; #pragma unroll
;         for (int e = 0; e < 8; e += 2) { const int s = s0 + 8 * q + e;
;             const float x0 = (s <= t) ? wv[e] * RS[s] : 0.f, x1 = (s + 1 <= t) ? wv[e + 1] * RS[s + 1] : 0.f;
;             const unsigned p = cvt_pk_bf16(x0, x1); pk[e >> 1] = p;
;             m2 += bf_lo(p) * MU[s] + bf_hi(p) * MU[s + 1]; }
;         *(LAS u32x4*)(WPb + t * 272 + (s0 + 8 * q) * 2) = (u32x4){pk[0], pk[1], pk[2], pk[3]}; }
;     m2 += __shfl_xor(m2, 1); m2 += __shfl_xor(m2, 2);
;     if (part == 0) M2b[t] = m2;
.LBB0_999:
	s_or_b64 exec, exec, s[92:93]
	s_and_saveexec_b64 s[92:93], s[66:67]
	s_cbranch_execz .LBB0_1001
	ds_read_b32 v64, v173 offset:116
	s_waitcnt lgkmcnt(0)
	v_mul_f32_e32 v108, v215, v64
.LBB0_1001:
	s_or_b64 exec, exec, s[92:93]
	v_cvt_pk_bf16_f32 v64, v109, v108
	ds_read_b64 v[108:109], v175 offset:112
	v_mov_b32_e32 v65, 0
	v_mov_b32_e32 v115, 0
	s_and_saveexec_b64 s[92:93], s[68:69]
	s_cbranch_execz .LBB0_1003
	ds_read_b32 v115, v173 offset:120
	s_waitcnt lgkmcnt(0)
	v_mul_f32_e32 v115, v216, v115
.LBB0_1003:
	s_or_b64 exec, exec, s[92:93]
	s_and_saveexec_b64 s[92:93], s[70:71]
	s_cbranch_execz .LBB0_1005
	ds_read_b32 v65, v173 offset:124
	s_waitcnt lgkmcnt(0)
	v_mul_f32_e32 v65, v217, v65
.LBB0_1005:
	s_or_b64 exec, exec, s[92:93]
	v_lshlrev_b32_e32 v66, 16, v46
	v_and_b32_e32 v46, 0xffff0000, v46
	s_waitcnt lgkmcnt(14)
	v_mul_f32_e32 v46, v69, v46
	v_fmac_f32_e32 v46, v68, v66
	v_lshlrev_b32_e32 v66, 16, v47
	v_and_b32_e32 v47, 0xffff0000, v47
	v_mul_f32_e32 v47, v79, v47
	v_add_f32_e32 v46, 0, v46
	v_fmac_f32_e32 v47, v78, v66
	v_add_f32_e32 v46, v46, v47
	v_lshlrev_b32_e32 v47, 16, v48
	v_and_b32_e32 v48, 0xffff0000, v48
	v_mul_f32_e32 v48, v81, v48
	v_fmac_f32_e32 v48, v80, v47
	v_add_f32_e32 v46, v46, v48
	v_and_b32_e32 v48, 0xffff0000, v49
	v_lshlrev_b32_e32 v47, 16, v49
	v_mul_f32_e32 v48, v83, v48
	v_fmac_f32_e32 v48, v82, v47
	v_add_f32_e32 v46, v46, v48
	v_and_b32_e32 v48, 0xffff0000, v54
	v_lshlrev_b32_e32 v47, 16, v54
	s_waitcnt lgkmcnt(12)
	v_mul_f32_e32 v48, v85, v48
	v_fmac_f32_e32 v48, v84, v47
	v_add_f32_e32 v46, v46, v48
	v_and_b32_e32 v48, 0xffff0000, v55
	v_lshlrev_b32_e32 v47, 16, v55
	s_waitcnt lgkmcnt(11)
	v_mul_f32_e32 v48, v91, v48
	v_fmac_f32_e32 v48, v90, v47
	v_add_f32_e32 v46, v46, v48
	v_and_b32_e32 v48, 0xffff0000, v56
	v_lshlrev_b32_e32 v47, 16, v56
	s_waitcnt lgkmcnt(10)
	v_mul_f32_e32 v48, v93, v48
	v_fmac_f32_e32 v48, v92, v47
	v_add_f32_e32 v46, v46, v48
	v_and_b32_e32 v48, 0xffff0000, v57
	v_lshlrev_b32_e32 v47, 16, v57
	s_waitcnt lgkmcnt(9)
	v_mul_f32_e32 v48, v95, v48
	v_fmac_f32_e32 v48, v94, v47
	v_add_f32_e32 v46, v46, v48
	v_and_b32_e32 v48, 0xffff0000, v58
	v_lshlrev_b32_e32 v47, 16, v58
	s_waitcnt lgkmcnt(7)
	v_mul_f32_e32 v48, v97, v48
	v_fmac_f32_e32 v48, v96, v47
	v_add_f32_e32 v46, v46, v48
	v_and_b32_e32 v48, 0xffff0000, v59
	v_lshlrev_b32_e32 v47, 16, v59
	s_waitcnt lgkmcnt(6)
	v_mul_f32_e32 v48, v103, v48
	v_fmac_f32_e32 v48, v102, v47
	v_add_f32_e32 v46, v46, v48
	v_and_b32_e32 v48, 0xffff0000, v60
	v_lshlrev_b32_e32 v47, 16, v60
	s_waitcnt lgkmcnt(5)
	v_mul_f32_e32 v48, v105, v48
	v_fmac_f32_e32 v48, v104, v47
	v_add_f32_e32 v46, v46, v48
	v_and_b32_e32 v48, 0xffff0000, v61
	v_lshlrev_b32_e32 v47, 16, v61
	s_waitcnt lgkmcnt(4)
	v_mul_f32_e32 v48, v107, v48
	v_fmac_f32_e32 v48, v106, v47
	v_add_f32_e32 v46, v46, v48
	v_and_b32_e32 v48, 0xffff0000, v62
	v_lshlrev_b32_e32 v47, 16, v62
	s_waitcnt lgkmcnt(2)
	v_mul_f32_e32 v48, v75, v48
	v_fmac_f32_e32 v48, v74, v47
	v_add_f32_e32 v46, v46, v48
	v_and_b32_e32 v48, 0xffff0000, v63
	v_lshlrev_b32_e32 v47, 16, v63
	s_waitcnt lgkmcnt(1)
	v_mul_f32_e32 v48, v77, v48
	v_fmac_f32_e32 v48, v76, v47
	v_add_f32_e32 v48, v46, v48
	v_and_b32_e32 v46, 0xffff0000, v64
	s_waitcnt lgkmcnt(0)
	v_mul_f32_e32 v54, v109, v46
	v_cvt_pk_bf16_f32 v65, v115, v65
	ds_read_b64 v[46:47], v175 offset:120
	v_lshlrev_b32_e32 v49, 16, v64
	v_fmac_f32_e32 v54, v108, v49
	v_add_f32_e32 v48, v48, v54
	v_and_b32_e32 v54, 0xffff0000, v65
	v_lshlrev_b32_e32 v49, 16, v65
	s_waitcnt lgkmcnt(0)
	v_mul_f32_e32 v47, v47, v54
	v_fmac_f32_e32 v47, v46, v49
	v_add_f32_e32 v46, v48, v47
	ds_bpermute_b32 v47, v225, v46
	ds_write_b128 v114, v[62:65] offset:48
	s_waitcnt lgkmcnt(1)
	v_add_f32_e32 v46, v46, v47
	ds_bpermute_b32 v47, v226, v46
	s_and_saveexec_b64 s[92:93], s[72:73]
	s_cbranch_execz .LBB0_1007
	v_lshl_add_u32 v48, s89, 9, v0
	s_waitcnt lgkmcnt(0)
	v_add_f32_e32 v46, v46, v47
	ds_write_b32 v48, v46

; #define LAS __attribute__((address_space(3)))
; template <class T> __device__ __forceinline__ T ntload(const T* p) { return __builtin_nontemporal_load(p); }
; __device__ __forceinline__ void spatial_phase(int j, const bf16_t* UG, bf16_t* Y, const bf16_t* Vt, LAS unsigned char* lds, int sw, View vw) {
;     ...
; #pragma unroll
;             for (int f = 0; f < 2; ++f)
; #pragma unroll
;                 for (int i = 0; i < 8; ++i) acc[f][i] = (f32x4){0.f, 0.f, 0.f, 0.f};
; #pragma unroll
;             for (int i = 0; i < 8; ++i)
; #pragma unroll
;                 for (int ks = 0; ks <= (i >> 1); ++ks) {
;                     const bf16x8 wf = *(const LAS bf16x8*)(WP + (16 * i + fr) * WPITCH + (32 * ks + 8 * fq) * 2);
; #pragma unroll
;                     for (int f = 0; f < 2; ++f) acc[f][i] = __builtin_amdgcn_mfma_f32_16x16x32_bf16(vf[f][ks], wf, acc[f][i], 0, 0, 0);
;                 }
;             if (g < 7) {
;                 const bf16_t* vp = Vt + ((size_t)chunk * E + ch0 + 256) * 128;
; #pragma unroll
;                 for (int f = 0; f < 2; ++f)
; #pragma unroll
;                     for (int ks = 0; ks < 4; ++ks) vf[f][ks] = ntload((const bf16x8*)(vp + (4 * f) * 128 + 32 * ks + vlo));
;             }
.LBB0_1008:
	s_mul_i32 s82, s95, 0x8800
	v_add3_u32 v62, v222, s82, v223
	s_waitcnt lgkmcnt(0)
	ds_read_b128 v[46:49], v62
	ds_read_b128 v[58:61], v62 offset:8768
	s_andn2_b64 vcc, exec, vcc
	s_waitcnt vmcnt(15) lgkmcnt(1)
	v_mfma_f32_16x16x32_bf16 v[134:137], v[2:5], v[46:49], 0
	s_waitcnt vmcnt(11)
	v_mfma_f32_16x16x32_bf16 v[130:133], v[18:21], v[46:49], 0
	ds_read_b128 v[46:49], v62 offset:4352
	s_waitcnt lgkmcnt(0)
	v_mfma_f32_16x16x32_bf16 v[126:129], v[2:5], v[46:49], 0
	v_mfma_f32_16x16x32_bf16 v[122:125], v[18:21], v[46:49], 0
	ds_read_b128 v[46:49], v62 offset:8704
	s_waitcnt lgkmcnt(0)
	v_mfma_f32_16x16x32_bf16 v[54:57], v[2:5], v[46:49], 0
	v_mfma_f32_16x16x32_bf16 v[46:49], v[18:21], v[46:49], 0
	s_waitcnt vmcnt(10)
	v_mfma_f32_16x16x32_bf16 v[114:117], v[22:25], v[58:61], v[46:49]
	v_mfma_f32_16x16x32_bf16 v[118:121], v[6:9], v[58:61], v[54:57]
	s_nop 4
	ds_read_b128 v[46:49], v62 offset:13056
	ds_read_b128 v[58:61], v62 offset:13120
	s_waitcnt lgkmcnt(1)
	v_mfma_f32_16x16x32_bf16 v[54:57], v[2:5], v[46:49], 0
	v_mfma_f32_16x16x32_bf16 v[46:49], v[18:21], v[46:49], 0
	s_waitcnt lgkmcnt(0)
	v_mfma_f32_16x16x32_bf16 v[102:105], v[22:25], v[58:61], v[46:49]
	v_mfma_f32_16x16x32_bf16 v[106:109], v[6:9], v[58:61], v[54:57]
	s_nop 4
	ds_read_b128 v[46:49], v62 offset:17408
	ds_read_b128 v[58:61], v62 offset:17472
	s_waitcnt lgkmcnt(1)
	v_mfma_f32_16x16x32_bf16 v[54:57], v[2:5], v[46:49], 0
	v_mfma_f32_16x16x32_bf16 v[46:49], v[18:21], v[46:49], 0
	s_waitcnt lgkmcnt(0)
	v_mfma_f32_16x16x32_bf16 v[54:57], v[6:9], v[58:61], v[54:57]
	v_mfma_f32_16x16x32_bf16 v[46:49], v[22:25], v[58:61], v[46:49]
	ds_read_b128 v[58:61], v62 offset:17536
	s_waitcnt vmcnt(9) lgkmcnt(0)
	v_mfma_f32_16x16x32_bf16 v[90:93], v[26:29], v[58:61], v[46:49]
	s_nop 4
	ds_read_b128 v[46:49], v62 offset:21760
	v_mfma_f32_16x16x32_bf16 v[94:97], v[10:13], v[58:61], v[54:57]
	ds_read_b128 v[58:61], v62 offset:21824
	s_waitcnt lgkmcnt(1)
	v_mfma_f32_16x16x32_bf16 v[54:57], v[2:5], v[46:49], 0
	v_mfma_f32_16x16x32_bf16 v[46:49], v[18:21], v[46:49], 0
	s_waitcnt lgkmcnt(0)
	v_mfma_f32_16x16x32_bf16 v[54:57], v[6:9], v[58:61], v[54:57]
	v_mfma_f32_16x16x32_bf16 v[46:49], v[22:25], v[58:61], v[46:49]
	ds_read_b128 v[58:61], v62 offset:21888
	s_waitcnt lgkmcnt(0)
	v_mfma_f32_16x16x32_bf16 v[78:81], v[26:29], v[58:61], v[46:49]
	s_nop 4
	ds_read_b128 v[46:49], v62 offset:26112
	v_mfma_f32_16x16x32_bf16 v[82:85], v[10:13], v[58:61], v[54:57]
	ds_read_b128 v[58:61], v62 offset:26176
	s_waitcnt lgkmcnt(1)
	v_mfma_f32_16x16x32_bf16 v[54:57], v[2:5], v[46:49], 0
	v_mfma_f32_16x16x32_bf16 v[46:49], v[18:21], v[46:49], 0
	s_waitcnt lgkmcnt(0)
	v_mfma_f32_16x16x32_bf16 v[54:57], v[6:9], v[58:61], v[54:57]
	v_mfma_f32_16x16x32_bf16 v[46:49], v[22:25], v[58:61], v[46:49]
	ds_read_b128 v[58:61], v62 offset:26240
	s_waitcnt lgkmcnt(0)
	v_mfma_f32_16x16x32_bf16 v[54:57], v[10:13], v[58:61], v[54:57]
	v_mfma_f32_16x16x32_bf16 v[46:49], v[26:29], v[58:61], v[46:49]
	ds_read_b128 v[58:61], v62 offset:26304
	s_waitcnt vmcnt(8) lgkmcnt(0)
	v_mfma_f32_16x16x32_bf16 v[66:69], v[30:33], v[58:61], v[46:49]
	s_nop 4
	ds_read_b128 v[46:49], v62 offset:30464
	v_mfma_f32_16x16x32_bf16 v[74:77], v[14:17], v[58:61], v[54:57]
	ds_read_b128 v[58:61], v62 offset:30528
	s_waitcnt lgkmcnt(1)
	v_mfma_f32_16x16x32_bf16 v[54:57], v[2:5], v[46:49], 0
	v_mfma_f32_16x16x32_bf16 v[46:49], v[18:21], v[46:49], 0
	s_waitcnt lgkmcnt(0)
	v_mfma_f32_16x16x32_bf16 v[54:57], v[6:9], v[58:61], v[54:57]
	v_mfma_f32_16x16x32_bf16 v[46:49], v[22:25], v[58:61], v[46:49]
	ds_read_b128 v[58:61], v62 offset:30592
	ds_read_b128 v[62:65], v62 offset:30656
	s_waitcnt lgkmcnt(1)
	v_mfma_f32_16x16x32_bf16 v[54:57], v[10:13], v[58:61], v[54:57]
	v_mfma_f32_16x16x32_bf16 v[46:49], v[26:29], v[58:61], v[46:49]
	s_waitcnt lgkmcnt(0)
	v_mfma_f32_16x16x32_bf16 v[58:61], v[14:17], v[62:65], v[54:57]
	v_mfma_f32_16x16x32_bf16 v[46:49], v[30:33], v[62:65], v[46:49]
	s_cbranch_vccnz .Lsp_g7
	global_load_dwordx4 v[2:5], v[162:163], off offset:-1024 nt
	global_load_dwordx4 v[6:9], v[162:163], off offset:-960 nt
	global_load_dwordx4 v[10:13], v[162:163], off offset:-896 nt
	global_load_dwordx4 v[14:17], v[162:163], off offset:-832 nt
	global_load_dwordx4 v[18:21], v[162:163], off nt
	global_load_dwordx4 v[22:25], v[162:163], off offset:64 nt
	global_load_dwordx4 v[26:29], v[162:163], off offset:128 nt
	global_load_dwordx4 v[30:33], v[162:163], off offset:192 nt
	s_waitcnt vmcnt(8)
	s_branch .LBB0_939
.Lsp_g7:
	s_waitcnt vmcnt(0)
	s_branch .LBB0_939
